# conversion item loop with 16 loads in flight (depth 2) instead of 32
# baseline (speedup 1.0000x reference)
.LBB0_20:
	v_lshl_add_u64 v[36:37], v[20:21], 0, s[20:21]
	v_lshl_add_u64 v[38:39], v[18:19], 0, s[20:21]
	v_lshl_add_u64 v[40:41], v[16:17], 0, s[20:21]
	v_lshl_add_u64 v[42:43], v[14:15], 0, s[20:21]
	v_lshl_add_u64 v[44:45], v[12:13], 0, s[20:21]
	v_lshl_add_u64 v[46:47], v[10:11], 0, s[20:21]
	v_lshl_add_u64 v[48:49], v[8:9], 0, s[20:21]
	v_lshl_add_u64 v[50:51], v[6:7], 0, s[20:21]
	global_load_dword v52, v[36:37], off nt
	global_load_dword v53, v[38:39], off nt
	global_load_dword v54, v[40:41], off nt
	global_load_dword v55, v[42:43], off nt
	global_load_dword v56, v[44:45], off nt
	global_load_dword v57, v[46:47], off nt
	global_load_dword v58, v[48:49], off nt
	global_load_dword v59, v[50:51], off nt
	s_add_u32 s20, s20, 0x20000
	s_addc_u32 s21, s21, 0
	v_lshl_add_u64 v[36:37], v[20:21], 0, s[20:21]
	v_lshl_add_u64 v[38:39], v[18:19], 0, s[20:21]
	v_lshl_add_u64 v[40:41], v[16:17], 0, s[20:21]
	v_lshl_add_u64 v[42:43], v[14:15], 0, s[20:21]
	v_lshl_add_u64 v[44:45], v[12:13], 0, s[20:21]
	v_lshl_add_u64 v[46:47], v[10:11], 0, s[20:21]
	v_lshl_add_u64 v[48:49], v[8:9], 0, s[20:21]
	v_lshl_add_u64 v[50:51], v[6:7], 0, s[20:21]
	global_load_dword v60, v[36:37], off nt
	global_load_dword v61, v[38:39], off nt
	global_load_dword v62, v[40:41], off nt
	global_load_dword v63, v[42:43], off nt
	global_load_dword v64, v[44:45], off nt
	global_load_dword v65, v[46:47], off nt
	global_load_dword v66, v[48:49], off nt
	global_load_dword v67, v[50:51], off nt
	s_add_u32 s20, s20, 0x20000
	s_addc_u32 s21, s21, 0
	v_add_u32_e32 v36, 0x400, v35
	s_waitcnt vmcnt(14)
	ds_write2_b32 v35, v52, v53 offset1:66
	s_waitcnt vmcnt(12)
	ds_write2_b32 v35, v54, v55 offset0:132 offset1:198
	s_waitcnt vmcnt(10)
	ds_write2_b32 v36, v56, v57 offset0:8 offset1:74
	s_waitcnt vmcnt(8)
	ds_write2_b32 v36, v58, v59 offset0:140 offset1:206
	v_add_u32_e32 v35, 0x840, v35
	v_add_u32_e32 v36, 0x400, v35
	s_waitcnt vmcnt(6)
	ds_write2_b32 v35, v60, v61 offset1:66
	s_waitcnt vmcnt(4)
	ds_write2_b32 v35, v62, v63 offset0:132 offset1:198
	s_waitcnt vmcnt(2)
	ds_write2_b32 v36, v64, v65 offset0:8 offset1:74
	s_waitcnt vmcnt(0)
	ds_write2_b32 v36, v66, v67 offset0:140 offset1:206
	v_add_u32_e32 v35, 0x840, v35
	v_lshl_add_u64 v[36:37], v[20:21], 0, s[20:21]
	v_lshl_add_u64 v[38:39], v[18:19], 0, s[20:21]
	v_lshl_add_u64 v[40:41], v[16:17], 0, s[20:21]
	v_lshl_add_u64 v[42:43], v[14:15], 0, s[20:21]
	v_lshl_add_u64 v[44:45], v[12:13], 0, s[20:21]
	v_lshl_add_u64 v[46:47], v[10:11], 0, s[20:21]
	v_lshl_add_u64 v[48:49], v[8:9], 0, s[20:21]
	v_lshl_add_u64 v[50:51], v[6:7], 0, s[20:21]
	global_load_dword v52, v[36:37], off nt
	global_load_dword v53, v[38:39], off nt
	global_load_dword v54, v[40:41], off nt
	global_load_dword v55, v[42:43], off nt
	global_load_dword v56, v[44:45], off nt
	global_load_dword v57, v[46:47], off nt
	global_load_dword v58, v[48:49], off nt
	global_load_dword v59, v[50:51], off nt
	s_add_u32 s20, s20, 0x20000
	s_addc_u32 s21, s21, 0
	v_lshl_add_u64 v[36:37], v[20:21], 0, s[20:21]
	v_lshl_add_u64 v[38:39], v[18:19], 0, s[20:21]
	v_lshl_add_u64 v[40:41], v[16:17], 0, s[20:21]
	v_lshl_add_u64 v[42:43], v[14:15], 0, s[20:21]
	v_lshl_add_u64 v[44:45], v[12:13], 0, s[20:21]
	v_lshl_add_u64 v[46:47], v[10:11], 0, s[20:21]
	v_lshl_add_u64 v[48:49], v[8:9], 0, s[20:21]
	v_lshl_add_u64 v[50:51], v[6:7], 0, s[20:21]
	global_load_dword v60, v[36:37], off nt
	global_load_dword v61, v[38:39], off nt
	global_load_dword v62, v[40:41], off nt
	global_load_dword v63, v[42:43], off nt
	global_load_dword v64, v[44:45], off nt
	global_load_dword v65, v[46:47], off nt
	global_load_dword v66, v[48:49], off nt
	global_load_dword v67, v[50:51], off nt
	s_add_u32 s20, s20, 0x20000
	s_addc_u32 s21, s21, 0
	v_add_u32_e32 v36, 0x400, v35
	s_waitcnt vmcnt(14)
	ds_write2_b32 v35, v52, v53 offset1:66
	s_waitcnt vmcnt(12)
	ds_write2_b32 v35, v54, v55 offset0:132 offset1:198
	s_waitcnt vmcnt(10)
	ds_write2_b32 v36, v56, v57 offset0:8 offset1:74
	s_waitcnt vmcnt(8)
	ds_write2_b32 v36, v58, v59 offset0:140 offset1:206
	v_add_u32_e32 v35, 0x840, v35
	v_add_u32_e32 v36, 0x400, v35
	s_waitcnt vmcnt(6)
	ds_write2_b32 v35, v60, v61 offset1:66
	s_waitcnt vmcnt(4)
	ds_write2_b32 v35, v62, v63 offset0:132 offset1:198
	s_waitcnt vmcnt(2)
	ds_write2_b32 v36, v64, v65 offset0:8 offset1:74
	s_waitcnt vmcnt(0)
	ds_write2_b32 v36, v66, v67 offset0:140 offset1:206
	v_add_u32_e32 v35, 0x840, v35
	s_waitcnt lgkmcnt(0)
	s_lshl_b32 s20, s22, 5
	ds_read2_b32 v[10:11], v23 offset1:8
	s_and_b32 s33, s20, 0x7e0
	s_lshl_b32 s20, s23, 1
	ds_read2_b32 v[14:15], v23 offset0:33 offset1:41
	s_add_u32 s20, s30, s20
	s_addc_u32 s21, s31, 0
	ds_read2_b32 v[16:17], v23 offset0:66 offset1:74
	v_lshl_add_u64 v[6:7], s[20:21], 0, v[2:3]
	ds_read2_b32 v[18:19], v23 offset0:99 offset1:107
	v_lshl_add_u64 v[12:13], v[6:7], 0, s[4:5]
	s_waitcnt lgkmcnt(3)
	v_bfe_u32 v6, v10, 16, 1
	v_add3_u32 v6, v10, v6, s26
	s_waitcnt lgkmcnt(2)
	v_bfe_u32 v7, v14, 16, 1
	ds_read2_b32 v[20:21], v23 offset0:132 offset1:140
	v_lshrrev_b32_e32 v6, 16, v6
	v_add3_u32 v7, v14, v7, s26
	ds_read2_b32 v[36:37], v23 offset0:165 offset1:173
	v_and_or_b32 v6, v7, s27, v6
	s_waitcnt lgkmcnt(3)
	v_bfe_u32 v7, v16, 16, 1
	v_add3_u32 v7, v16, v7, s26
	s_waitcnt lgkmcnt(2)
	v_bfe_u32 v8, v18, 16, 1
	ds_read2_b32 v[38:39], v23 offset0:198 offset1:206
	v_lshrrev_b32_e32 v7, 16, v7
	v_add3_u32 v8, v18, v8, s26
	ds_read2_b32 v[40:41], v23 offset0:231 offset1:239
	v_and_or_b32 v7, v8, s27, v7
	s_waitcnt lgkmcnt(3)
	v_bfe_u32 v8, v20, 16, 1
	v_add3_u32 v8, v20, v8, s26
	s_waitcnt lgkmcnt(2)
	v_bfe_u32 v9, v36, 16, 1
	v_lshrrev_b32_e32 v8, 16, v8
	v_add3_u32 v9, v36, v9, s26
	v_and_or_b32 v8, v9, s27, v8
	s_waitcnt lgkmcnt(1)
	v_bfe_u32 v9, v38, 16, 1
	v_add3_u32 v9, v38, v9, s26
	s_waitcnt lgkmcnt(0)
	v_bfe_u32 v10, v40, 16, 1
	v_lshrrev_b32_e32 v9, 16, v9
	v_add3_u32 v10, v40, v10, s26
	v_and_or_b32 v9, v10, s27, v9
	v_or_b32_e32 v10, s33, v22
	v_mul_u32_u24_e32 v10, 0x1600, v10
	v_lshlrev_b32_e32 v42, 1, v10
	v_mov_b32_e32 v43, v3
	v_lshl_add_u64 v[42:43], v[12:13], 0, v[42:43]
	global_store_dwordx4 v[42:43], v[6:9], off
	v_bfe_u32 v10, v41, 16, 1
	v_add3_u32 v10, v41, v10, s26
	v_bfe_u32 v6, v11, 16, 1
	v_add3_u32 v6, v11, v6, s26
	v_bfe_u32 v7, v15, 16, 1
	v_lshrrev_b32_e32 v6, 16, v6
	v_add3_u32 v7, v15, v7, s26
	v_and_or_b32 v6, v7, s27, v6
	v_bfe_u32 v7, v17, 16, 1
	v_add3_u32 v7, v17, v7, s26
	v_bfe_u32 v8, v19, 16, 1
	v_lshrrev_b32_e32 v7, 16, v7
	v_add3_u32 v8, v19, v8, s26
	v_and_or_b32 v7, v8, s27, v7
	v_bfe_u32 v8, v21, 16, 1
	v_add3_u32 v8, v21, v8, s26
	v_bfe_u32 v9, v37, 16, 1
	v_lshrrev_b32_e32 v8, 16, v8
	v_add3_u32 v9, v37, v9, s26
	v_and_or_b32 v8, v9, s27, v8
	v_bfe_u32 v9, v39, 16, 1
	v_add3_u32 v9, v39, v9, s26
	v_lshrrev_b32_e32 v9, 16, v9
	v_and_or_b32 v9, v10, s27, v9
	v_or_b32_e32 v10, s33, v24
	v_mul_u32_u24_e32 v10, 0x1600, v10
	v_lshlrev_b32_e32 v10, 1, v10
	v_mov_b32_e32 v11, v3
	ds_read2_b32 v[14:15], v23 offset0:16 offset1:24
	v_lshl_add_u64 v[10:11], v[12:13], 0, v[10:11]
	global_store_dwordx4 v[10:11], v[6:9], off
	ds_read2_b32 v[10:11], v23 offset0:49 offset1:57
	ds_read2_b32 v[16:17], v23 offset0:82 offset1:90
	ds_read2_b32 v[18:19], v23 offset0:115 offset1:123
	s_waitcnt lgkmcnt(3)
	v_bfe_u32 v6, v14, 16, 1
	v_add3_u32 v6, v14, v6, s26
	s_waitcnt lgkmcnt(2)
	v_bfe_u32 v7, v10, 16, 1
	ds_read2_b32 v[20:21], v23 offset0:148 offset1:156
	v_lshrrev_b32_e32 v6, 16, v6
	v_add3_u32 v7, v10, v7, s26
	ds_read2_b32 v[36:37], v23 offset0:181 offset1:189
	v_and_or_b32 v6, v7, s27, v6
	s_waitcnt lgkmcnt(3)
	v_bfe_u32 v7, v16, 16, 1
	v_add3_u32 v7, v16, v7, s26
	s_waitcnt lgkmcnt(2)
	v_bfe_u32 v8, v18, 16, 1
	ds_read2_b32 v[38:39], v23 offset0:214 offset1:222
	v_lshrrev_b32_e32 v7, 16, v7
	v_add3_u32 v8, v18, v8, s26
	ds_read2_b32 v[40:41], v23 offset0:247 offset1:255
	v_and_or_b32 v7, v8, s27, v7
	s_waitcnt lgkmcnt(3)
	v_bfe_u32 v8, v20, 16, 1
	v_add3_u32 v8, v20, v8, s26
	s_waitcnt lgkmcnt(2)
	v_bfe_u32 v9, v36, 16, 1
	v_lshrrev_b32_e32 v8, 16, v8
	v_add3_u32 v9, v36, v9, s26
	v_and_or_b32 v8, v9, s27, v8
	s_waitcnt lgkmcnt(1)
	v_bfe_u32 v9, v38, 16, 1
	v_add3_u32 v9, v38, v9, s26
	s_waitcnt lgkmcnt(0)
	v_bfe_u32 v10, v40, 16, 1
	v_lshrrev_b32_e32 v9, 16, v9
	v_add3_u32 v10, v40, v10, s26
	v_and_or_b32 v9, v10, s27, v9
	v_or_b32_e32 v10, s33, v25
	v_mul_u32_u24_e32 v10, 0x1600, v10
	v_lshlrev_b32_e32 v42, 1, v10
	v_mov_b32_e32 v43, v3
	v_lshl_add_u64 v[42:43], v[12:13], 0, v[42:43]
	global_store_dwordx4 v[42:43], v[6:9], off
	v_bfe_u32 v10, v41, 16, 1
	v_add3_u32 v10, v41, v10, s26
	v_bfe_u32 v6, v15, 16, 1
	v_add3_u32 v6, v15, v6, s26
	v_bfe_u32 v7, v11, 16, 1
	v_lshrrev_b32_e32 v6, 16, v6
	v_add3_u32 v7, v11, v7, s26
	v_and_or_b32 v6, v7, s27, v6
	v_bfe_u32 v7, v17, 16, 1
	v_add3_u32 v7, v17, v7, s26
	v_bfe_u32 v8, v19, 16, 1
	v_lshrrev_b32_e32 v7, 16, v7
	v_add3_u32 v8, v19, v8, s26
	v_and_or_b32 v7, v8, s27, v7
	v_bfe_u32 v8, v21, 16, 1
	v_add3_u32 v8, v21, v8, s26
	v_bfe_u32 v9, v37, 16, 1
	v_lshrrev_b32_e32 v8, 16, v8
	v_add3_u32 v9, v37, v9, s26
	v_and_or_b32 v8, v9, s27, v8
	v_bfe_u32 v9, v39, 16, 1
	v_add3_u32 v9, v39, v9, s26
	v_lshrrev_b32_e32 v9, 16, v9
	v_and_or_b32 v9, v10, s27, v9
	v_or_b32_e32 v10, s33, v26
	v_mul_u32_u24_e32 v10, 0x1600, v10
	v_lshlrev_b32_e32 v10, 1, v10
	v_mov_b32_e32 v11, v3
	v_lshl_add_u64 v[10:11], v[12:13], 0, v[10:11]
	global_store_dwordx4 v[10:11], v[6:9], off
	s_waitcnt lgkmcnt(0)
	s_mov_b64 s[20:21], 0

.LBB0_24:
	v_lshl_add_u64 v[36:37], v[20:21], 0, s[20:21]
	v_lshl_add_u64 v[38:39], v[18:19], 0, s[20:21]
	v_lshl_add_u64 v[40:41], v[16:17], 0, s[20:21]
	v_lshl_add_u64 v[42:43], v[14:15], 0, s[20:21]
	v_lshl_add_u64 v[44:45], v[12:13], 0, s[20:21]
	v_lshl_add_u64 v[46:47], v[10:11], 0, s[20:21]
	v_lshl_add_u64 v[48:49], v[8:9], 0, s[20:21]
	v_lshl_add_u64 v[50:51], v[6:7], 0, s[20:21]
	global_load_dword v52, v[36:37], off nt
	global_load_dword v53, v[38:39], off nt
	global_load_dword v54, v[40:41], off nt
	global_load_dword v55, v[42:43], off nt
	global_load_dword v56, v[44:45], off nt
	global_load_dword v57, v[46:47], off nt
	global_load_dword v58, v[48:49], off nt
	global_load_dword v59, v[50:51], off nt
	s_add_u32 s20, s20, 0x58000
	s_addc_u32 s21, s21, 0
	v_lshl_add_u64 v[36:37], v[20:21], 0, s[20:21]
	v_lshl_add_u64 v[38:39], v[18:19], 0, s[20:21]
	v_lshl_add_u64 v[40:41], v[16:17], 0, s[20:21]
	v_lshl_add_u64 v[42:43], v[14:15], 0, s[20:21]
	v_lshl_add_u64 v[44:45], v[12:13], 0, s[20:21]
	v_lshl_add_u64 v[46:47], v[10:11], 0, s[20:21]
	v_lshl_add_u64 v[48:49], v[8:9], 0, s[20:21]
	v_lshl_add_u64 v[50:51], v[6:7], 0, s[20:21]
	global_load_dword v60, v[36:37], off nt
	global_load_dword v61, v[38:39], off nt
	global_load_dword v62, v[40:41], off nt
	global_load_dword v63, v[42:43], off nt
	global_load_dword v64, v[44:45], off nt
	global_load_dword v65, v[46:47], off nt
	global_load_dword v66, v[48:49], off nt
	global_load_dword v67, v[50:51], off nt
	s_add_u32 s20, s20, 0x58000
	s_addc_u32 s21, s21, 0
	v_add_u32_e32 v36, 0x400, v35
	s_waitcnt vmcnt(14)
	ds_write2_b32 v35, v52, v53 offset1:66
	s_waitcnt vmcnt(12)
	ds_write2_b32 v35, v54, v55 offset0:132 offset1:198
	s_waitcnt vmcnt(10)
	ds_write2_b32 v36, v56, v57 offset0:8 offset1:74
	s_waitcnt vmcnt(8)
	ds_write2_b32 v36, v58, v59 offset0:140 offset1:206
	v_add_u32_e32 v35, 0x840, v35
	v_add_u32_e32 v36, 0x400, v35
	s_waitcnt vmcnt(6)
	ds_write2_b32 v35, v60, v61 offset1:66
	s_waitcnt vmcnt(4)
	ds_write2_b32 v35, v62, v63 offset0:132 offset1:198
	s_waitcnt vmcnt(2)
	ds_write2_b32 v36, v64, v65 offset0:8 offset1:74
	s_waitcnt vmcnt(0)
	ds_write2_b32 v36, v66, v67 offset0:140 offset1:206
	v_add_u32_e32 v35, 0x840, v35
	v_lshl_add_u64 v[36:37], v[20:21], 0, s[20:21]
	v_lshl_add_u64 v[38:39], v[18:19], 0, s[20:21]
	v_lshl_add_u64 v[40:41], v[16:17], 0, s[20:21]
	v_lshl_add_u64 v[42:43], v[14:15], 0, s[20:21]
	v_lshl_add_u64 v[44:45], v[12:13], 0, s[20:21]
	v_lshl_add_u64 v[46:47], v[10:11], 0, s[20:21]
	v_lshl_add_u64 v[48:49], v[8:9], 0, s[20:21]
	v_lshl_add_u64 v[50:51], v[6:7], 0, s[20:21]
	global_load_dword v52, v[36:37], off nt
	global_load_dword v53, v[38:39], off nt
	global_load_dword v54, v[40:41], off nt
	global_load_dword v55, v[42:43], off nt
	global_load_dword v56, v[44:45], off nt
	global_load_dword v57, v[46:47], off nt
	global_load_dword v58, v[48:49], off nt
	global_load_dword v59, v[50:51], off nt
	s_add_u32 s20, s20, 0x58000
	s_addc_u32 s21, s21, 0
	v_lshl_add_u64 v[36:37], v[20:21], 0, s[20:21]
	v_lshl_add_u64 v[38:39], v[18:19], 0, s[20:21]
	v_lshl_add_u64 v[40:41], v[16:17], 0, s[20:21]
	v_lshl_add_u64 v[42:43], v[14:15], 0, s[20:21]
	v_lshl_add_u64 v[44:45], v[12:13], 0, s[20:21]
	v_lshl_add_u64 v[46:47], v[10:11], 0, s[20:21]
	v_lshl_add_u64 v[48:49], v[8:9], 0, s[20:21]
	v_lshl_add_u64 v[50:51], v[6:7], 0, s[20:21]
	global_load_dword v60, v[36:37], off nt
	global_load_dword v61, v[38:39], off nt
	global_load_dword v62, v[40:41], off nt
	global_load_dword v63, v[42:43], off nt
	global_load_dword v64, v[44:45], off nt
	global_load_dword v65, v[46:47], off nt
	global_load_dword v66, v[48:49], off nt
	global_load_dword v67, v[50:51], off nt
	s_add_u32 s20, s20, 0x58000
	s_addc_u32 s21, s21, 0
	v_add_u32_e32 v36, 0x400, v35
	s_waitcnt vmcnt(14)
	ds_write2_b32 v35, v52, v53 offset1:66
	s_waitcnt vmcnt(12)
	ds_write2_b32 v35, v54, v55 offset0:132 offset1:198
	s_waitcnt vmcnt(10)
	ds_write2_b32 v36, v56, v57 offset0:8 offset1:74
	s_waitcnt vmcnt(8)
	ds_write2_b32 v36, v58, v59 offset0:140 offset1:206
	v_add_u32_e32 v35, 0x840, v35
	v_add_u32_e32 v36, 0x400, v35
	s_waitcnt vmcnt(6)
	ds_write2_b32 v35, v60, v61 offset1:66
	s_waitcnt vmcnt(4)
	ds_write2_b32 v35, v62, v63 offset0:132 offset1:198
	s_waitcnt vmcnt(2)
	ds_write2_b32 v36, v64, v65 offset0:8 offset1:74
	s_waitcnt vmcnt(0)
	ds_write2_b32 v36, v66, v67 offset0:140 offset1:206
	v_add_u32_e32 v35, 0x840, v35
	s_lshl_b32 s20, s33, 5
	s_lshl_b32 s21, s33, 6
	s_and_b32 s21, s21, 0x3f00
	s_and_b32 s20, s20, 0x60
	s_waitcnt lgkmcnt(0)
	s_or_b32 s20, s21, s20
	s_or_b32 s33, s20, 0x80
	s_and_b32 s20, 0xffff, s23
	ds_read2_b32 v[10:11], v23 offset1:8
	s_lshl_b32 s20, s20, 1
	ds_read2_b32 v[14:15], v23 offset0:33 offset1:41
	s_add_u32 s20, s30, s20
	s_addc_u32 s21, s31, 0
	ds_read2_b32 v[16:17], v23 offset0:66 offset1:74
	v_lshl_add_u64 v[6:7], s[20:21], 0, v[2:3]
	ds_read2_b32 v[18:19], v23 offset0:99 offset1:107
	v_lshl_add_u64 v[12:13], v[6:7], 0, s[6:7]
	s_waitcnt lgkmcnt(3)
	v_bfe_u32 v6, v10, 16, 1
	v_add3_u32 v6, v10, v6, s26
	s_waitcnt lgkmcnt(2)
	v_bfe_u32 v7, v14, 16, 1
	ds_read2_b32 v[20:21], v23 offset0:132 offset1:140
	v_lshrrev_b32_e32 v6, 16, v6
	v_add3_u32 v7, v14, v7, s26
	ds_read2_b32 v[36:37], v23 offset0:165 offset1:173
	v_and_or_b32 v6, v7, s27, v6
	s_waitcnt lgkmcnt(3)
	v_bfe_u32 v7, v16, 16, 1
	v_add3_u32 v7, v16, v7, s26
	s_waitcnt lgkmcnt(2)
	v_bfe_u32 v8, v18, 16, 1
	ds_read2_b32 v[38:39], v23 offset0:198 offset1:206
	v_lshrrev_b32_e32 v7, 16, v7
	v_add3_u32 v8, v18, v8, s26
	ds_read2_b32 v[40:41], v23 offset0:231 offset1:239
	v_and_or_b32 v7, v8, s27, v7
	s_waitcnt lgkmcnt(3)
	v_bfe_u32 v8, v20, 16, 1
	v_add3_u32 v8, v20, v8, s26
	s_waitcnt lgkmcnt(2)
	v_bfe_u32 v9, v36, 16, 1
	v_lshrrev_b32_e32 v8, 16, v8
	v_add3_u32 v9, v36, v9, s26
	v_and_or_b32 v8, v9, s27, v8
	s_waitcnt lgkmcnt(1)
	v_bfe_u32 v9, v38, 16, 1
	v_add3_u32 v9, v38, v9, s26
	s_waitcnt lgkmcnt(0)
	v_bfe_u32 v10, v40, 16, 1
	v_lshrrev_b32_e32 v9, 16, v9
	v_add3_u32 v10, v40, v10, s26
	v_and_or_b32 v9, v10, s27, v9
	v_or_b32_e32 v10, s33, v22
	v_lshlrev_b32_e32 v42, 12, v10
	v_mov_b32_e32 v43, v3
	v_lshl_add_u64 v[42:43], v[12:13], 0, v[42:43]
	global_store_dwordx4 v[42:43], v[6:9], off
	v_bfe_u32 v10, v41, 16, 1
	v_add3_u32 v10, v41, v10, s26
	v_bfe_u32 v6, v11, 16, 1
	v_add3_u32 v6, v11, v6, s26
	v_bfe_u32 v7, v15, 16, 1
	v_lshrrev_b32_e32 v6, 16, v6
	v_add3_u32 v7, v15, v7, s26
	v_and_or_b32 v6, v7, s27, v6
	v_bfe_u32 v7, v17, 16, 1
	v_add3_u32 v7, v17, v7, s26
	v_bfe_u32 v8, v19, 16, 1
	v_lshrrev_b32_e32 v7, 16, v7
	v_add3_u32 v8, v19, v8, s26
	v_and_or_b32 v7, v8, s27, v7
	v_bfe_u32 v8, v21, 16, 1
	v_add3_u32 v8, v21, v8, s26
	v_bfe_u32 v9, v37, 16, 1
	v_lshrrev_b32_e32 v8, 16, v8
	v_add3_u32 v9, v37, v9, s26
	v_and_or_b32 v8, v9, s27, v8
	v_bfe_u32 v9, v39, 16, 1
	v_add3_u32 v9, v39, v9, s26
	v_lshrrev_b32_e32 v9, 16, v9
	v_and_or_b32 v9, v10, s27, v9
	v_or_b32_e32 v10, s33, v24
	v_lshlrev_b32_e32 v10, 12, v10
	v_mov_b32_e32 v11, v3
	ds_read2_b32 v[14:15], v23 offset0:16 offset1:24
	v_lshl_add_u64 v[10:11], v[12:13], 0, v[10:11]
	global_store_dwordx4 v[10:11], v[6:9], off
	ds_read2_b32 v[10:11], v23 offset0:49 offset1:57
	ds_read2_b32 v[16:17], v23 offset0:82 offset1:90
	ds_read2_b32 v[18:19], v23 offset0:115 offset1:123
	s_waitcnt lgkmcnt(3)
	v_bfe_u32 v6, v14, 16, 1
	v_add3_u32 v6, v14, v6, s26
	s_waitcnt lgkmcnt(2)
	v_bfe_u32 v7, v10, 16, 1
	ds_read2_b32 v[20:21], v23 offset0:148 offset1:156
	v_lshrrev_b32_e32 v6, 16, v6
	v_add3_u32 v7, v10, v7, s26
	ds_read2_b32 v[36:37], v23 offset0:181 offset1:189
	v_and_or_b32 v6, v7, s27, v6
	s_waitcnt lgkmcnt(3)
	v_bfe_u32 v7, v16, 16, 1
	v_add3_u32 v7, v16, v7, s26
	s_waitcnt lgkmcnt(2)
	v_bfe_u32 v8, v18, 16, 1
	ds_read2_b32 v[38:39], v23 offset0:214 offset1:222
	v_lshrrev_b32_e32 v7, 16, v7
	v_add3_u32 v8, v18, v8, s26
	ds_read2_b32 v[40:41], v23 offset0:247 offset1:255
	v_and_or_b32 v7, v8, s27, v7
	s_waitcnt lgkmcnt(3)
	v_bfe_u32 v8, v20, 16, 1
	v_add3_u32 v8, v20, v8, s26
	s_waitcnt lgkmcnt(2)
	v_bfe_u32 v9, v36, 16, 1
	v_lshrrev_b32_e32 v8, 16, v8
	v_add3_u32 v9, v36, v9, s26
	v_and_or_b32 v8, v9, s27, v8
	s_waitcnt lgkmcnt(1)
	v_bfe_u32 v9, v38, 16, 1
	v_add3_u32 v9, v38, v9, s26
	s_waitcnt lgkmcnt(0)
	v_bfe_u32 v10, v40, 16, 1
	v_lshrrev_b32_e32 v9, 16, v9
	v_add3_u32 v10, v40, v10, s26
	v_and_or_b32 v9, v10, s27, v9
	v_or_b32_e32 v10, s33, v25
	v_lshlrev_b32_e32 v42, 12, v10
	v_mov_b32_e32 v43, v3
	v_lshl_add_u64 v[42:43], v[12:13], 0, v[42:43]
	global_store_dwordx4 v[42:43], v[6:9], off
	v_bfe_u32 v10, v41, 16, 1
	v_add3_u32 v10, v41, v10, s26
	v_bfe_u32 v6, v15, 16, 1
	v_add3_u32 v6, v15, v6, s26
	v_bfe_u32 v7, v11, 16, 1
	v_lshrrev_b32_e32 v6, 16, v6
	v_add3_u32 v7, v11, v7, s26
	v_and_or_b32 v6, v7, s27, v6
	v_bfe_u32 v7, v17, 16, 1
	v_add3_u32 v7, v17, v7, s26
	v_bfe_u32 v8, v19, 16, 1
	v_lshrrev_b32_e32 v7, 16, v7
	v_add3_u32 v8, v19, v8, s26
	v_and_or_b32 v7, v8, s27, v7
	v_bfe_u32 v8, v21, 16, 1
	v_add3_u32 v8, v21, v8, s26
	v_bfe_u32 v9, v37, 16, 1
	v_lshrrev_b32_e32 v8, 16, v8
	v_add3_u32 v9, v37, v9, s26
	v_and_or_b32 v8, v9, s27, v8
	v_bfe_u32 v9, v39, 16, 1
	v_add3_u32 v9, v39, v9, s26
	v_lshrrev_b32_e32 v9, 16, v9
	v_and_or_b32 v9, v10, s27, v9
	v_or_b32_e32 v10, s33, v26
	v_lshlrev_b32_e32 v10, 12, v10
	v_mov_b32_e32 v11, v3
	v_lshl_add_u64 v[10:11], v[12:13], 0, v[10:11]
	global_store_dwordx4 v[10:11], v[6:9], off
	s_waitcnt lgkmcnt(0)

.LBB0_29:
	v_lshl_add_u64 v[36:37], v[20:21], 0, s[20:21]
	v_lshl_add_u64 v[38:39], v[18:19], 0, s[20:21]
	v_lshl_add_u64 v[40:41], v[16:17], 0, s[20:21]
	v_lshl_add_u64 v[42:43], v[14:15], 0, s[20:21]
	v_lshl_add_u64 v[44:45], v[12:13], 0, s[20:21]
	v_lshl_add_u64 v[46:47], v[10:11], 0, s[20:21]
	v_lshl_add_u64 v[48:49], v[8:9], 0, s[20:21]
	v_lshl_add_u64 v[50:51], v[6:7], 0, s[20:21]
	global_load_dword v52, v[36:37], off nt
	global_load_dword v53, v[38:39], off nt
	global_load_dword v54, v[40:41], off nt
	global_load_dword v55, v[42:43], off nt
	global_load_dword v56, v[44:45], off nt
	global_load_dword v57, v[46:47], off nt
	global_load_dword v58, v[48:49], off nt
	global_load_dword v59, v[50:51], off nt
	s_add_u32 s20, s20, 0x58000
	s_addc_u32 s21, s21, 0
	v_lshl_add_u64 v[36:37], v[20:21], 0, s[20:21]
	v_lshl_add_u64 v[38:39], v[18:19], 0, s[20:21]
	v_lshl_add_u64 v[40:41], v[16:17], 0, s[20:21]
	v_lshl_add_u64 v[42:43], v[14:15], 0, s[20:21]
	v_lshl_add_u64 v[44:45], v[12:13], 0, s[20:21]
	v_lshl_add_u64 v[46:47], v[10:11], 0, s[20:21]
	v_lshl_add_u64 v[48:49], v[8:9], 0, s[20:21]
	v_lshl_add_u64 v[50:51], v[6:7], 0, s[20:21]
	global_load_dword v60, v[36:37], off nt
	global_load_dword v61, v[38:39], off nt
	global_load_dword v62, v[40:41], off nt
	global_load_dword v63, v[42:43], off nt
	global_load_dword v64, v[44:45], off nt
	global_load_dword v65, v[46:47], off nt
	global_load_dword v66, v[48:49], off nt
	global_load_dword v67, v[50:51], off nt
	s_add_u32 s20, s20, 0x58000
	s_addc_u32 s21, s21, 0
	v_add_u32_e32 v36, 0x400, v35
	s_waitcnt vmcnt(14)
	ds_write2_b32 v35, v52, v53 offset1:66
	s_waitcnt vmcnt(12)
	ds_write2_b32 v35, v54, v55 offset0:132 offset1:198
	s_waitcnt vmcnt(10)
	ds_write2_b32 v36, v56, v57 offset0:8 offset1:74
	s_waitcnt vmcnt(8)
	ds_write2_b32 v36, v58, v59 offset0:140 offset1:206
	v_add_u32_e32 v35, 0x840, v35
	v_add_u32_e32 v36, 0x400, v35
	s_waitcnt vmcnt(6)
	ds_write2_b32 v35, v60, v61 offset1:66
	s_waitcnt vmcnt(4)
	ds_write2_b32 v35, v62, v63 offset0:132 offset1:198
	s_waitcnt vmcnt(2)
	ds_write2_b32 v36, v64, v65 offset0:8 offset1:74
	s_waitcnt vmcnt(0)
	ds_write2_b32 v36, v66, v67 offset0:140 offset1:206
	v_add_u32_e32 v35, 0x840, v35
	v_lshl_add_u64 v[36:37], v[20:21], 0, s[20:21]
	v_lshl_add_u64 v[38:39], v[18:19], 0, s[20:21]
	v_lshl_add_u64 v[40:41], v[16:17], 0, s[20:21]
	v_lshl_add_u64 v[42:43], v[14:15], 0, s[20:21]
	v_lshl_add_u64 v[44:45], v[12:13], 0, s[20:21]
	v_lshl_add_u64 v[46:47], v[10:11], 0, s[20:21]
	v_lshl_add_u64 v[48:49], v[8:9], 0, s[20:21]
	v_lshl_add_u64 v[50:51], v[6:7], 0, s[20:21]
	global_load_dword v52, v[36:37], off nt
	global_load_dword v53, v[38:39], off nt
	global_load_dword v54, v[40:41], off nt
	global_load_dword v55, v[42:43], off nt
	global_load_dword v56, v[44:45], off nt
	global_load_dword v57, v[46:47], off nt
	global_load_dword v58, v[48:49], off nt
	global_load_dword v59, v[50:51], off nt
	s_add_u32 s20, s20, 0x58000
	s_addc_u32 s21, s21, 0
	v_lshl_add_u64 v[36:37], v[20:21], 0, s[20:21]
	v_lshl_add_u64 v[38:39], v[18:19], 0, s[20:21]
	v_lshl_add_u64 v[40:41], v[16:17], 0, s[20:21]
	v_lshl_add_u64 v[42:43], v[14:15], 0, s[20:21]
	v_lshl_add_u64 v[44:45], v[12:13], 0, s[20:21]
	v_lshl_add_u64 v[46:47], v[10:11], 0, s[20:21]
	v_lshl_add_u64 v[48:49], v[8:9], 0, s[20:21]
	v_lshl_add_u64 v[50:51], v[6:7], 0, s[20:21]
	global_load_dword v60, v[36:37], off nt
	global_load_dword v61, v[38:39], off nt
	global_load_dword v62, v[40:41], off nt
	global_load_dword v63, v[42:43], off nt
	global_load_dword v64, v[44:45], off nt
	global_load_dword v65, v[46:47], off nt
	global_load_dword v66, v[48:49], off nt
	global_load_dword v67, v[50:51], off nt
	s_add_u32 s20, s20, 0x58000
	s_addc_u32 s21, s21, 0
	v_add_u32_e32 v36, 0x400, v35
	s_waitcnt vmcnt(14)
	ds_write2_b32 v35, v52, v53 offset1:66
	s_waitcnt vmcnt(12)
	ds_write2_b32 v35, v54, v55 offset0:132 offset1:198
	s_waitcnt vmcnt(10)
	ds_write2_b32 v36, v56, v57 offset0:8 offset1:74
	s_waitcnt vmcnt(8)
	ds_write2_b32 v36, v58, v59 offset0:140 offset1:206
	v_add_u32_e32 v35, 0x840, v35
	v_add_u32_e32 v36, 0x400, v35
	s_waitcnt vmcnt(6)
	ds_write2_b32 v35, v60, v61 offset1:66
	s_waitcnt vmcnt(4)
	ds_write2_b32 v35, v62, v63 offset0:132 offset1:198
	s_waitcnt vmcnt(2)
	ds_write2_b32 v36, v64, v65 offset0:8 offset1:74
	s_waitcnt vmcnt(0)
	ds_write2_b32 v36, v66, v67 offset0:140 offset1:206
	v_add_u32_e32 v35, 0x840, v35
	s_lshl_b32 s20, s33, 5
	s_lshl_b32 s21, s33, 6
	s_waitcnt lgkmcnt(0)
	s_and_b32 s21, s21, 0x3f00
	s_and_b32 s20, s20, 0x60
	s_or_b32 s33, s20, s21
	s_and_b32 s20, 0xffff, s23
	ds_read2_b32 v[10:11], v23 offset1:8
	s_lshl_b32 s20, s20, 1
	ds_read2_b32 v[14:15], v23 offset0:33 offset1:41
	s_add_u32 s20, s30, s20
	s_addc_u32 s21, s31, 0
	ds_read2_b32 v[16:17], v23 offset0:66 offset1:74
	v_lshl_add_u64 v[6:7], s[20:21], 0, v[2:3]
	ds_read2_b32 v[18:19], v23 offset0:99 offset1:107
	v_lshl_add_u64 v[12:13], v[6:7], 0, s[6:7]
	s_waitcnt lgkmcnt(3)
	v_bfe_u32 v6, v10, 16, 1
	v_add3_u32 v6, v10, v6, s26
	s_waitcnt lgkmcnt(2)
	v_bfe_u32 v7, v14, 16, 1
	ds_read2_b32 v[20:21], v23 offset0:132 offset1:140
	v_lshrrev_b32_e32 v6, 16, v6
	v_add3_u32 v7, v14, v7, s26
	ds_read2_b32 v[36:37], v23 offset0:165 offset1:173
	v_and_or_b32 v6, v7, s27, v6
	s_waitcnt lgkmcnt(3)
	v_bfe_u32 v7, v16, 16, 1
	v_add3_u32 v7, v16, v7, s26
	s_waitcnt lgkmcnt(2)
	v_bfe_u32 v8, v18, 16, 1
	ds_read2_b32 v[38:39], v23 offset0:198 offset1:206
	v_lshrrev_b32_e32 v7, 16, v7
	v_add3_u32 v8, v18, v8, s26
	ds_read2_b32 v[40:41], v23 offset0:231 offset1:239
	v_and_or_b32 v7, v8, s27, v7
	s_waitcnt lgkmcnt(3)
	v_bfe_u32 v8, v20, 16, 1
	v_add3_u32 v8, v20, v8, s26
	s_waitcnt lgkmcnt(2)
	v_bfe_u32 v9, v36, 16, 1
	v_lshrrev_b32_e32 v8, 16, v8
	v_add3_u32 v9, v36, v9, s26
	v_and_or_b32 v8, v9, s27, v8
	s_waitcnt lgkmcnt(1)
	v_bfe_u32 v9, v38, 16, 1
	v_add3_u32 v9, v38, v9, s26
	s_waitcnt lgkmcnt(0)
	v_bfe_u32 v10, v40, 16, 1
	v_lshrrev_b32_e32 v9, 16, v9
	v_add3_u32 v10, v40, v10, s26
	v_and_or_b32 v9, v10, s27, v9
	v_or_b32_e32 v10, s33, v22
	v_lshlrev_b32_e32 v42, 12, v10
	v_mov_b32_e32 v43, v3
	v_lshl_add_u64 v[42:43], v[12:13], 0, v[42:43]
	global_store_dwordx4 v[42:43], v[6:9], off
	v_bfe_u32 v10, v41, 16, 1
	v_add3_u32 v10, v41, v10, s26
	v_bfe_u32 v6, v11, 16, 1
	v_add3_u32 v6, v11, v6, s26
	v_bfe_u32 v7, v15, 16, 1
	v_lshrrev_b32_e32 v6, 16, v6
	v_add3_u32 v7, v15, v7, s26
	v_and_or_b32 v6, v7, s27, v6
	v_bfe_u32 v7, v17, 16, 1
	v_add3_u32 v7, v17, v7, s26
	v_bfe_u32 v8, v19, 16, 1
	v_lshrrev_b32_e32 v7, 16, v7
	v_add3_u32 v8, v19, v8, s26
	v_and_or_b32 v7, v8, s27, v7
	v_bfe_u32 v8, v21, 16, 1
	v_add3_u32 v8, v21, v8, s26
	v_bfe_u32 v9, v37, 16, 1
	v_lshrrev_b32_e32 v8, 16, v8
	v_add3_u32 v9, v37, v9, s26
	v_and_or_b32 v8, v9, s27, v8
	v_bfe_u32 v9, v39, 16, 1
	v_add3_u32 v9, v39, v9, s26
	v_lshrrev_b32_e32 v9, 16, v9
	v_and_or_b32 v9, v10, s27, v9
	v_or_b32_e32 v10, s33, v24
	v_lshlrev_b32_e32 v10, 12, v10
	v_mov_b32_e32 v11, v3
	ds_read2_b32 v[14:15], v23 offset0:16 offset1:24
	v_lshl_add_u64 v[10:11], v[12:13], 0, v[10:11]
	global_store_dwordx4 v[10:11], v[6:9], off
	ds_read2_b32 v[10:11], v23 offset0:49 offset1:57
	ds_read2_b32 v[16:17], v23 offset0:82 offset1:90
	ds_read2_b32 v[18:19], v23 offset0:115 offset1:123
	s_waitcnt lgkmcnt(3)
	v_bfe_u32 v6, v14, 16, 1
	v_add3_u32 v6, v14, v6, s26
	s_waitcnt lgkmcnt(2)
	v_bfe_u32 v7, v10, 16, 1
	ds_read2_b32 v[20:21], v23 offset0:148 offset1:156
	v_lshrrev_b32_e32 v6, 16, v6
	v_add3_u32 v7, v10, v7, s26
	ds_read2_b32 v[36:37], v23 offset0:181 offset1:189
	v_and_or_b32 v6, v7, s27, v6
	s_waitcnt lgkmcnt(3)
	v_bfe_u32 v7, v16, 16, 1
	v_add3_u32 v7, v16, v7, s26
	s_waitcnt lgkmcnt(2)
	v_bfe_u32 v8, v18, 16, 1
	ds_read2_b32 v[38:39], v23 offset0:214 offset1:222
	v_lshrrev_b32_e32 v7, 16, v7
	v_add3_u32 v8, v18, v8, s26
	ds_read2_b32 v[40:41], v23 offset0:247 offset1:255
	v_and_or_b32 v7, v8, s27, v7
	s_waitcnt lgkmcnt(3)
	v_bfe_u32 v8, v20, 16, 1
	v_add3_u32 v8, v20, v8, s26
	s_waitcnt lgkmcnt(2)
	v_bfe_u32 v9, v36, 16, 1
	v_lshrrev_b32_e32 v8, 16, v8
	v_add3_u32 v9, v36, v9, s26
	v_and_or_b32 v8, v9, s27, v8
	s_waitcnt lgkmcnt(1)
	v_bfe_u32 v9, v38, 16, 1
	v_add3_u32 v9, v38, v9, s26
	s_waitcnt lgkmcnt(0)
	v_bfe_u32 v10, v40, 16, 1
	v_lshrrev_b32_e32 v9, 16, v9
	v_add3_u32 v10, v40, v10, s26
	v_and_or_b32 v9, v10, s27, v9
	v_or_b32_e32 v10, s33, v25
	v_lshlrev_b32_e32 v42, 12, v10
	v_mov_b32_e32 v43, v3
	v_lshl_add_u64 v[42:43], v[12:13], 0, v[42:43]
	global_store_dwordx4 v[42:43], v[6:9], off
	v_bfe_u32 v10, v41, 16, 1
	v_add3_u32 v10, v41, v10, s26
	v_bfe_u32 v6, v15, 16, 1
	v_add3_u32 v6, v15, v6, s26
	v_bfe_u32 v7, v11, 16, 1
	v_lshrrev_b32_e32 v6, 16, v6
	v_add3_u32 v7, v11, v7, s26
	v_and_or_b32 v6, v7, s27, v6
	v_bfe_u32 v7, v17, 16, 1
	v_add3_u32 v7, v17, v7, s26
	v_bfe_u32 v8, v19, 16, 1
	v_lshrrev_b32_e32 v7, 16, v7
	v_add3_u32 v8, v19, v8, s26
	v_and_or_b32 v7, v8, s27, v7
	v_bfe_u32 v8, v21, 16, 1
	v_add3_u32 v8, v21, v8, s26
	v_bfe_u32 v9, v37, 16, 1
	v_lshrrev_b32_e32 v8, 16, v8
	v_add3_u32 v9, v37, v9, s26
	v_and_or_b32 v8, v9, s27, v8
	v_bfe_u32 v9, v39, 16, 1
	v_add3_u32 v9, v39, v9, s26
	v_lshrrev_b32_e32 v9, 16, v9
	v_and_or_b32 v9, v10, s27, v9
	v_or_b32_e32 v10, s33, v26
	v_lshlrev_b32_e32 v10, 12, v10
	v_mov_b32_e32 v11, v3
	v_lshl_add_u64 v[10:11], v[12:13], 0, v[10:11]
	global_store_dwordx4 v[10:11], v[6:9], off
	s_waitcnt lgkmcnt(0)

.LBB0_34:
	v_lshl_add_u64 v[36:37], v[20:21], 0, s[20:21]
	v_lshl_add_u64 v[38:39], v[18:19], 0, s[20:21]
	v_lshl_add_u64 v[40:41], v[16:17], 0, s[20:21]
	v_lshl_add_u64 v[42:43], v[14:15], 0, s[20:21]
	v_lshl_add_u64 v[44:45], v[12:13], 0, s[20:21]
	v_lshl_add_u64 v[46:47], v[10:11], 0, s[20:21]
	v_lshl_add_u64 v[48:49], v[8:9], 0, s[20:21]
	v_lshl_add_u64 v[50:51], v[6:7], 0, s[20:21]
	global_load_dword v52, v[36:37], off nt
	global_load_dword v53, v[38:39], off nt
	global_load_dword v54, v[40:41], off nt
	global_load_dword v55, v[42:43], off nt
	global_load_dword v56, v[44:45], off nt
	global_load_dword v57, v[46:47], off nt
	global_load_dword v58, v[48:49], off nt
	global_load_dword v59, v[50:51], off nt
	s_add_u32 s20, s20, 0x8000
	s_addc_u32 s21, s21, 0
	v_lshl_add_u64 v[36:37], v[20:21], 0, s[20:21]
	v_lshl_add_u64 v[38:39], v[18:19], 0, s[20:21]
	v_lshl_add_u64 v[40:41], v[16:17], 0, s[20:21]
	v_lshl_add_u64 v[42:43], v[14:15], 0, s[20:21]
	v_lshl_add_u64 v[44:45], v[12:13], 0, s[20:21]
	v_lshl_add_u64 v[46:47], v[10:11], 0, s[20:21]
	v_lshl_add_u64 v[48:49], v[8:9], 0, s[20:21]
	v_lshl_add_u64 v[50:51], v[6:7], 0, s[20:21]
	global_load_dword v60, v[36:37], off nt
	global_load_dword v61, v[38:39], off nt
	global_load_dword v62, v[40:41], off nt
	global_load_dword v63, v[42:43], off nt
	global_load_dword v64, v[44:45], off nt
	global_load_dword v65, v[46:47], off nt
	global_load_dword v66, v[48:49], off nt
	global_load_dword v67, v[50:51], off nt
	s_add_u32 s20, s20, 0x8000
	s_addc_u32 s21, s21, 0
	v_add_u32_e32 v36, 0x400, v35
	s_waitcnt vmcnt(14)
	ds_write2_b32 v35, v52, v53 offset1:66
	s_waitcnt vmcnt(12)
	ds_write2_b32 v35, v54, v55 offset0:132 offset1:198
	s_waitcnt vmcnt(10)
	ds_write2_b32 v36, v56, v57 offset0:8 offset1:74
	s_waitcnt vmcnt(8)
	ds_write2_b32 v36, v58, v59 offset0:140 offset1:206
	v_add_u32_e32 v35, 0x840, v35
	v_add_u32_e32 v36, 0x400, v35
	s_waitcnt vmcnt(6)
	ds_write2_b32 v35, v60, v61 offset1:66
	s_waitcnt vmcnt(4)
	ds_write2_b32 v35, v62, v63 offset0:132 offset1:198
	s_waitcnt vmcnt(2)
	ds_write2_b32 v36, v64, v65 offset0:8 offset1:74
	s_waitcnt vmcnt(0)
	ds_write2_b32 v36, v66, v67 offset0:140 offset1:206
	v_add_u32_e32 v35, 0x840, v35
	v_lshl_add_u64 v[36:37], v[20:21], 0, s[20:21]
	v_lshl_add_u64 v[38:39], v[18:19], 0, s[20:21]
	v_lshl_add_u64 v[40:41], v[16:17], 0, s[20:21]
	v_lshl_add_u64 v[42:43], v[14:15], 0, s[20:21]
	v_lshl_add_u64 v[44:45], v[12:13], 0, s[20:21]
	v_lshl_add_u64 v[46:47], v[10:11], 0, s[20:21]
	v_lshl_add_u64 v[48:49], v[8:9], 0, s[20:21]
	v_lshl_add_u64 v[50:51], v[6:7], 0, s[20:21]
	global_load_dword v52, v[36:37], off nt
	global_load_dword v53, v[38:39], off nt
	global_load_dword v54, v[40:41], off nt
	global_load_dword v55, v[42:43], off nt
	global_load_dword v56, v[44:45], off nt
	global_load_dword v57, v[46:47], off nt
	global_load_dword v58, v[48:49], off nt
	global_load_dword v59, v[50:51], off nt
	s_add_u32 s20, s20, 0x8000
	s_addc_u32 s21, s21, 0
	v_lshl_add_u64 v[36:37], v[20:21], 0, s[20:21]
	v_lshl_add_u64 v[38:39], v[18:19], 0, s[20:21]
	v_lshl_add_u64 v[40:41], v[16:17], 0, s[20:21]
	v_lshl_add_u64 v[42:43], v[14:15], 0, s[20:21]
	v_lshl_add_u64 v[44:45], v[12:13], 0, s[20:21]
	v_lshl_add_u64 v[46:47], v[10:11], 0, s[20:21]
	v_lshl_add_u64 v[48:49], v[8:9], 0, s[20:21]
	v_lshl_add_u64 v[50:51], v[6:7], 0, s[20:21]
	global_load_dword v60, v[36:37], off nt
	global_load_dword v61, v[38:39], off nt
	global_load_dword v62, v[40:41], off nt
	global_load_dword v63, v[42:43], off nt
	global_load_dword v64, v[44:45], off nt
	global_load_dword v65, v[46:47], off nt
	global_load_dword v66, v[48:49], off nt
	global_load_dword v67, v[50:51], off nt
	s_add_u32 s20, s20, 0x8000
	s_addc_u32 s21, s21, 0
	v_add_u32_e32 v36, 0x400, v35
	s_waitcnt vmcnt(14)
	ds_write2_b32 v35, v52, v53 offset1:66
	s_waitcnt vmcnt(12)
	ds_write2_b32 v35, v54, v55 offset0:132 offset1:198
	s_waitcnt vmcnt(10)
	ds_write2_b32 v36, v56, v57 offset0:8 offset1:74
	s_waitcnt vmcnt(8)
	ds_write2_b32 v36, v58, v59 offset0:140 offset1:206
	v_add_u32_e32 v35, 0x840, v35
	v_add_u32_e32 v36, 0x400, v35
	s_waitcnt vmcnt(6)
	ds_write2_b32 v35, v60, v61 offset1:66
	s_waitcnt vmcnt(4)
	ds_write2_b32 v35, v62, v63 offset0:132 offset1:198
	s_waitcnt vmcnt(2)
	ds_write2_b32 v36, v64, v65 offset0:8 offset1:74
	s_waitcnt vmcnt(0)
	ds_write2_b32 v36, v66, v67 offset0:140 offset1:206
	v_add_u32_e32 v35, 0x840, v35
	s_waitcnt lgkmcnt(0)
	s_lshl_b32 s20, s22, 5
	ds_read2_b32 v[10:11], v23 offset1:8
	s_and_b32 s33, s20, 0x1e0
	s_lshl_b32 s20, s23, 1
	ds_read2_b32 v[14:15], v23 offset0:33 offset1:41
	s_add_u32 s20, s30, s20
	s_addc_u32 s21, s31, 0
	ds_read2_b32 v[16:17], v23 offset0:66 offset1:74
	v_lshl_add_u64 v[6:7], s[20:21], 0, v[2:3]
	ds_read2_b32 v[18:19], v23 offset0:99 offset1:107
	v_lshl_add_u64 v[12:13], v[6:7], 0, s[38:39]
	s_waitcnt lgkmcnt(3)
	v_bfe_u32 v6, v10, 16, 1
	v_add3_u32 v6, v10, v6, s26
	s_waitcnt lgkmcnt(2)
	v_bfe_u32 v7, v14, 16, 1
	ds_read2_b32 v[20:21], v23 offset0:132 offset1:140
	v_lshrrev_b32_e32 v6, 16, v6
	v_add3_u32 v7, v14, v7, s26
	ds_read2_b32 v[36:37], v23 offset0:165 offset1:173
	v_and_or_b32 v6, v7, s27, v6
	s_waitcnt lgkmcnt(3)
	v_bfe_u32 v7, v16, 16, 1
	v_add3_u32 v7, v16, v7, s26
	s_waitcnt lgkmcnt(2)
	v_bfe_u32 v8, v18, 16, 1
	ds_read2_b32 v[38:39], v23 offset0:198 offset1:206
	v_lshrrev_b32_e32 v7, 16, v7
	v_add3_u32 v8, v18, v8, s26
	ds_read2_b32 v[40:41], v23 offset0:231 offset1:239
	v_and_or_b32 v7, v8, s27, v7
	s_waitcnt lgkmcnt(3)
	v_bfe_u32 v8, v20, 16, 1
	v_add3_u32 v8, v20, v8, s26
	s_waitcnt lgkmcnt(2)
	v_bfe_u32 v9, v36, 16, 1
	v_lshrrev_b32_e32 v8, 16, v8
	v_add3_u32 v9, v36, v9, s26
	v_and_or_b32 v8, v9, s27, v8
	s_waitcnt lgkmcnt(1)
	v_bfe_u32 v9, v38, 16, 1
	v_add3_u32 v9, v38, v9, s26
	s_waitcnt lgkmcnt(0)
	v_bfe_u32 v10, v40, 16, 1
	v_lshrrev_b32_e32 v9, 16, v9
	v_add3_u32 v10, v40, v10, s26
	v_and_or_b32 v9, v10, s27, v9
	v_or_b32_e32 v10, s33, v22
	v_lshlrev_b32_e32 v42, 10, v10
	v_mov_b32_e32 v43, v3
	v_lshl_add_u64 v[42:43], v[12:13], 0, v[42:43]
	global_store_dwordx4 v[42:43], v[6:9], off
	v_bfe_u32 v10, v41, 16, 1
	v_add3_u32 v10, v41, v10, s26
	v_bfe_u32 v6, v11, 16, 1
	v_add3_u32 v6, v11, v6, s26
	v_bfe_u32 v7, v15, 16, 1
	v_lshrrev_b32_e32 v6, 16, v6
	v_add3_u32 v7, v15, v7, s26
	v_and_or_b32 v6, v7, s27, v6
	v_bfe_u32 v7, v17, 16, 1
	v_add3_u32 v7, v17, v7, s26
	v_bfe_u32 v8, v19, 16, 1
	v_lshrrev_b32_e32 v7, 16, v7
	v_add3_u32 v8, v19, v8, s26
	v_and_or_b32 v7, v8, s27, v7
	v_bfe_u32 v8, v21, 16, 1
	v_add3_u32 v8, v21, v8, s26
	v_bfe_u32 v9, v37, 16, 1
	v_lshrrev_b32_e32 v8, 16, v8
	v_add3_u32 v9, v37, v9, s26
	v_and_or_b32 v8, v9, s27, v8
	v_bfe_u32 v9, v39, 16, 1
	v_add3_u32 v9, v39, v9, s26
	v_lshrrev_b32_e32 v9, 16, v9
	v_and_or_b32 v9, v10, s27, v9
	v_or_b32_e32 v10, s33, v24
	v_lshlrev_b32_e32 v10, 10, v10
	v_mov_b32_e32 v11, v3
	ds_read2_b32 v[14:15], v23 offset0:16 offset1:24
	v_lshl_add_u64 v[10:11], v[12:13], 0, v[10:11]
	global_store_dwordx4 v[10:11], v[6:9], off
	ds_read2_b32 v[10:11], v23 offset0:49 offset1:57
	ds_read2_b32 v[16:17], v23 offset0:82 offset1:90
	ds_read2_b32 v[18:19], v23 offset0:115 offset1:123
	s_waitcnt lgkmcnt(3)
	v_bfe_u32 v6, v14, 16, 1
	v_add3_u32 v6, v14, v6, s26
	s_waitcnt lgkmcnt(2)
	v_bfe_u32 v7, v10, 16, 1
	ds_read2_b32 v[20:21], v23 offset0:148 offset1:156
	v_lshrrev_b32_e32 v6, 16, v6
	v_add3_u32 v7, v10, v7, s26
	ds_read2_b32 v[36:37], v23 offset0:181 offset1:189
	v_and_or_b32 v6, v7, s27, v6
	s_waitcnt lgkmcnt(3)
	v_bfe_u32 v7, v16, 16, 1
	v_add3_u32 v7, v16, v7, s26
	s_waitcnt lgkmcnt(2)
	v_bfe_u32 v8, v18, 16, 1
	ds_read2_b32 v[38:39], v23 offset0:214 offset1:222
	v_lshrrev_b32_e32 v7, 16, v7
	v_add3_u32 v8, v18, v8, s26
	ds_read2_b32 v[40:41], v23 offset0:247 offset1:255
	v_and_or_b32 v7, v8, s27, v7
	s_waitcnt lgkmcnt(3)
	v_bfe_u32 v8, v20, 16, 1
	v_add3_u32 v8, v20, v8, s26
	s_waitcnt lgkmcnt(2)
	v_bfe_u32 v9, v36, 16, 1
	v_lshrrev_b32_e32 v8, 16, v8
	v_add3_u32 v9, v36, v9, s26
	v_and_or_b32 v8, v9, s27, v8
	s_waitcnt lgkmcnt(1)
	v_bfe_u32 v9, v38, 16, 1
	v_add3_u32 v9, v38, v9, s26
	s_waitcnt lgkmcnt(0)
	v_bfe_u32 v10, v40, 16, 1
	v_lshrrev_b32_e32 v9, 16, v9
	v_add3_u32 v10, v40, v10, s26
	v_and_or_b32 v9, v10, s27, v9
	v_or_b32_e32 v10, s33, v25
	v_lshlrev_b32_e32 v42, 10, v10
	v_mov_b32_e32 v43, v3
	v_lshl_add_u64 v[42:43], v[12:13], 0, v[42:43]
	global_store_dwordx4 v[42:43], v[6:9], off
	v_bfe_u32 v10, v41, 16, 1
	v_add3_u32 v10, v41, v10, s26
	v_bfe_u32 v6, v15, 16, 1
	v_add3_u32 v6, v15, v6, s26
	v_bfe_u32 v7, v11, 16, 1
	v_lshrrev_b32_e32 v6, 16, v6
	v_add3_u32 v7, v11, v7, s26
	v_and_or_b32 v6, v7, s27, v6
	v_bfe_u32 v7, v17, 16, 1
	v_add3_u32 v7, v17, v7, s26
	v_bfe_u32 v8, v19, 16, 1
	v_lshrrev_b32_e32 v7, 16, v7
	v_add3_u32 v8, v19, v8, s26
	v_and_or_b32 v7, v8, s27, v7
	v_bfe_u32 v8, v21, 16, 1
	v_add3_u32 v8, v21, v8, s26
	v_bfe_u32 v9, v37, 16, 1
	v_lshrrev_b32_e32 v8, 16, v8
	v_add3_u32 v9, v37, v9, s26
	v_and_or_b32 v8, v9, s27, v8
	v_bfe_u32 v9, v39, 16, 1
	v_add3_u32 v9, v39, v9, s26
	v_lshrrev_b32_e32 v9, 16, v9
	v_and_or_b32 v9, v10, s27, v9
	v_or_b32_e32 v10, s33, v26
	v_lshlrev_b32_e32 v10, 10, v10
	v_mov_b32_e32 v11, v3
	v_lshl_add_u64 v[10:11], v[12:13], 0, v[10:11]
	global_store_dwordx4 v[10:11], v[6:9], off
	s_waitcnt lgkmcnt(0)

.LBB0_39:
	v_lshl_add_u64 v[36:37], v[20:21], 0, s[20:21]
	v_lshl_add_u64 v[38:39], v[18:19], 0, s[20:21]
	v_lshl_add_u64 v[40:41], v[16:17], 0, s[20:21]
	v_lshl_add_u64 v[42:43], v[14:15], 0, s[20:21]
	v_lshl_add_u64 v[44:45], v[12:13], 0, s[20:21]
	v_lshl_add_u64 v[46:47], v[10:11], 0, s[20:21]
	v_lshl_add_u64 v[48:49], v[8:9], 0, s[20:21]
	v_lshl_add_u64 v[50:51], v[6:7], 0, s[20:21]
	global_load_dword v52, v[36:37], off nt
	global_load_dword v53, v[38:39], off nt
	global_load_dword v54, v[40:41], off nt
	global_load_dword v55, v[42:43], off nt
	global_load_dword v56, v[44:45], off nt
	global_load_dword v57, v[46:47], off nt
	global_load_dword v58, v[48:49], off nt
	global_load_dword v59, v[50:51], off nt
	s_add_u32 s20, s20, 0x20000
	s_addc_u32 s21, s21, 0
	v_lshl_add_u64 v[36:37], v[20:21], 0, s[20:21]
	v_lshl_add_u64 v[38:39], v[18:19], 0, s[20:21]
	v_lshl_add_u64 v[40:41], v[16:17], 0, s[20:21]
	v_lshl_add_u64 v[42:43], v[14:15], 0, s[20:21]
	v_lshl_add_u64 v[44:45], v[12:13], 0, s[20:21]
	v_lshl_add_u64 v[46:47], v[10:11], 0, s[20:21]
	v_lshl_add_u64 v[48:49], v[8:9], 0, s[20:21]
	v_lshl_add_u64 v[50:51], v[6:7], 0, s[20:21]
	global_load_dword v60, v[36:37], off nt
	global_load_dword v61, v[38:39], off nt
	global_load_dword v62, v[40:41], off nt
	global_load_dword v63, v[42:43], off nt
	global_load_dword v64, v[44:45], off nt
	global_load_dword v65, v[46:47], off nt
	global_load_dword v66, v[48:49], off nt
	global_load_dword v67, v[50:51], off nt
	s_add_u32 s20, s20, 0x20000
	s_addc_u32 s21, s21, 0
	v_add_u32_e32 v36, 0x400, v35
	s_waitcnt vmcnt(14)
	ds_write2_b32 v35, v52, v53 offset1:66
	s_waitcnt vmcnt(12)
	ds_write2_b32 v35, v54, v55 offset0:132 offset1:198
	s_waitcnt vmcnt(10)
	ds_write2_b32 v36, v56, v57 offset0:8 offset1:74
	s_waitcnt vmcnt(8)
	ds_write2_b32 v36, v58, v59 offset0:140 offset1:206
	v_add_u32_e32 v35, 0x840, v35
	v_add_u32_e32 v36, 0x400, v35
	s_waitcnt vmcnt(6)
	ds_write2_b32 v35, v60, v61 offset1:66
	s_waitcnt vmcnt(4)
	ds_write2_b32 v35, v62, v63 offset0:132 offset1:198
	s_waitcnt vmcnt(2)
	ds_write2_b32 v36, v64, v65 offset0:8 offset1:74
	s_waitcnt vmcnt(0)
	ds_write2_b32 v36, v66, v67 offset0:140 offset1:206
	v_add_u32_e32 v35, 0x840, v35
	v_lshl_add_u64 v[36:37], v[20:21], 0, s[20:21]
	v_lshl_add_u64 v[38:39], v[18:19], 0, s[20:21]
	v_lshl_add_u64 v[40:41], v[16:17], 0, s[20:21]
	v_lshl_add_u64 v[42:43], v[14:15], 0, s[20:21]
	v_lshl_add_u64 v[44:45], v[12:13], 0, s[20:21]
	v_lshl_add_u64 v[46:47], v[10:11], 0, s[20:21]
	v_lshl_add_u64 v[48:49], v[8:9], 0, s[20:21]
	v_lshl_add_u64 v[50:51], v[6:7], 0, s[20:21]
	global_load_dword v52, v[36:37], off nt
	global_load_dword v53, v[38:39], off nt
	global_load_dword v54, v[40:41], off nt
	global_load_dword v55, v[42:43], off nt
	global_load_dword v56, v[44:45], off nt
	global_load_dword v57, v[46:47], off nt
	global_load_dword v58, v[48:49], off nt
	global_load_dword v59, v[50:51], off nt
	s_add_u32 s20, s20, 0x20000
	s_addc_u32 s21, s21, 0
	v_lshl_add_u64 v[36:37], v[20:21], 0, s[20:21]
	v_lshl_add_u64 v[38:39], v[18:19], 0, s[20:21]
	v_lshl_add_u64 v[40:41], v[16:17], 0, s[20:21]
	v_lshl_add_u64 v[42:43], v[14:15], 0, s[20:21]
	v_lshl_add_u64 v[44:45], v[12:13], 0, s[20:21]
	v_lshl_add_u64 v[46:47], v[10:11], 0, s[20:21]
	v_lshl_add_u64 v[48:49], v[8:9], 0, s[20:21]
	v_lshl_add_u64 v[50:51], v[6:7], 0, s[20:21]
	global_load_dword v60, v[36:37], off nt
	global_load_dword v61, v[38:39], off nt
	global_load_dword v62, v[40:41], off nt
	global_load_dword v63, v[42:43], off nt
	global_load_dword v64, v[44:45], off nt
	global_load_dword v65, v[46:47], off nt
	global_load_dword v66, v[48:49], off nt
	global_load_dword v67, v[50:51], off nt
	s_add_u32 s20, s20, 0x20000
	s_addc_u32 s21, s21, 0
	v_add_u32_e32 v36, 0x400, v35
	s_waitcnt vmcnt(14)
	ds_write2_b32 v35, v52, v53 offset1:66
	s_waitcnt vmcnt(12)
	ds_write2_b32 v35, v54, v55 offset0:132 offset1:198
	s_waitcnt vmcnt(10)
	ds_write2_b32 v36, v56, v57 offset0:8 offset1:74
	s_waitcnt vmcnt(8)
	ds_write2_b32 v36, v58, v59 offset0:140 offset1:206
	v_add_u32_e32 v35, 0x840, v35
	v_add_u32_e32 v36, 0x400, v35
	s_waitcnt vmcnt(6)
	ds_write2_b32 v35, v60, v61 offset1:66
	s_waitcnt vmcnt(4)
	ds_write2_b32 v35, v62, v63 offset0:132 offset1:198
	s_waitcnt vmcnt(2)
	ds_write2_b32 v36, v64, v65 offset0:8 offset1:74
	s_waitcnt vmcnt(0)
	ds_write2_b32 v36, v66, v67 offset0:140 offset1:206
	v_add_u32_e32 v35, 0x840, v35
	s_waitcnt lgkmcnt(0)
	s_lshl_b32 s20, s22, 5
	ds_read2_b32 v[10:11], v23 offset1:8
	s_and_b32 s23, s20, 0x7e0
	s_lshl_b32 s19, s19, 1
	ds_read2_b32 v[14:15], v23 offset0:33 offset1:41
	s_add_u32 s20, s30, s19
	s_addc_u32 s21, s31, 0
	ds_read2_b32 v[16:17], v23 offset0:66 offset1:74
	v_lshl_add_u64 v[6:7], s[20:21], 0, v[2:3]
	ds_read2_b32 v[18:19], v23 offset0:99 offset1:107
	v_lshl_add_u64 v[12:13], v[6:7], 0, s[12:13]
	s_waitcnt lgkmcnt(3)
	v_bfe_u32 v6, v10, 16, 1
	v_add3_u32 v6, v10, v6, s26
	s_waitcnt lgkmcnt(2)
	v_bfe_u32 v7, v14, 16, 1
	ds_read2_b32 v[20:21], v23 offset0:132 offset1:140
	v_lshrrev_b32_e32 v6, 16, v6
	v_add3_u32 v7, v14, v7, s26
	ds_read2_b32 v[36:37], v23 offset0:165 offset1:173
	v_and_or_b32 v6, v7, s27, v6
	s_waitcnt lgkmcnt(3)
	v_bfe_u32 v7, v16, 16, 1
	v_add3_u32 v7, v16, v7, s26
	s_waitcnt lgkmcnt(2)
	v_bfe_u32 v8, v18, 16, 1
	ds_read2_b32 v[38:39], v23 offset0:198 offset1:206
	v_lshrrev_b32_e32 v7, 16, v7
	v_add3_u32 v8, v18, v8, s26
	ds_read2_b32 v[40:41], v23 offset0:231 offset1:239
	v_and_or_b32 v7, v8, s27, v7
	s_waitcnt lgkmcnt(3)
	v_bfe_u32 v8, v20, 16, 1
	v_add3_u32 v8, v20, v8, s26
	s_waitcnt lgkmcnt(2)
	v_bfe_u32 v9, v36, 16, 1
	v_lshrrev_b32_e32 v8, 16, v8
	v_add3_u32 v9, v36, v9, s26
	v_and_or_b32 v8, v9, s27, v8
	s_waitcnt lgkmcnt(1)
	v_bfe_u32 v9, v38, 16, 1
	v_add3_u32 v9, v38, v9, s26
	s_waitcnt lgkmcnt(0)
	v_bfe_u32 v10, v40, 16, 1
	v_lshrrev_b32_e32 v9, 16, v9
	v_add3_u32 v10, v40, v10, s26
	v_and_or_b32 v9, v10, s27, v9
	v_or_b32_e32 v10, s23, v22
	v_lshlrev_b32_e32 v42, 12, v10
	v_mov_b32_e32 v43, v3
	v_lshl_add_u64 v[42:43], v[12:13], 0, v[42:43]
	global_store_dwordx4 v[42:43], v[6:9], off
	v_bfe_u32 v10, v41, 16, 1
	v_add3_u32 v10, v41, v10, s26
	v_bfe_u32 v6, v11, 16, 1
	v_add3_u32 v6, v11, v6, s26
	v_bfe_u32 v7, v15, 16, 1
	v_lshrrev_b32_e32 v6, 16, v6
	v_add3_u32 v7, v15, v7, s26
	v_and_or_b32 v6, v7, s27, v6
	v_bfe_u32 v7, v17, 16, 1
	v_add3_u32 v7, v17, v7, s26
	v_bfe_u32 v8, v19, 16, 1
	v_lshrrev_b32_e32 v7, 16, v7
	v_add3_u32 v8, v19, v8, s26
	v_and_or_b32 v7, v8, s27, v7
	v_bfe_u32 v8, v21, 16, 1
	v_add3_u32 v8, v21, v8, s26
	v_bfe_u32 v9, v37, 16, 1
	v_lshrrev_b32_e32 v8, 16, v8
	v_add3_u32 v9, v37, v9, s26
	v_and_or_b32 v8, v9, s27, v8
	v_bfe_u32 v9, v39, 16, 1
	v_add3_u32 v9, v39, v9, s26
	v_lshrrev_b32_e32 v9, 16, v9
	v_and_or_b32 v9, v10, s27, v9
	v_or_b32_e32 v10, s23, v24
	v_lshlrev_b32_e32 v10, 12, v10
	v_mov_b32_e32 v11, v3
	ds_read2_b32 v[14:15], v23 offset0:16 offset1:24
	v_lshl_add_u64 v[10:11], v[12:13], 0, v[10:11]
	global_store_dwordx4 v[10:11], v[6:9], off
	ds_read2_b32 v[10:11], v23 offset0:49 offset1:57
	ds_read2_b32 v[16:17], v23 offset0:82 offset1:90
	ds_read2_b32 v[18:19], v23 offset0:115 offset1:123
	s_waitcnt lgkmcnt(3)
	v_bfe_u32 v6, v14, 16, 1
	v_add3_u32 v6, v14, v6, s26
	s_waitcnt lgkmcnt(2)
	v_bfe_u32 v7, v10, 16, 1
	ds_read2_b32 v[20:21], v23 offset0:148 offset1:156
	v_lshrrev_b32_e32 v6, 16, v6
	v_add3_u32 v7, v10, v7, s26
	ds_read2_b32 v[36:37], v23 offset0:181 offset1:189
	v_and_or_b32 v6, v7, s27, v6
	s_waitcnt lgkmcnt(3)
	v_bfe_u32 v7, v16, 16, 1
	v_add3_u32 v7, v16, v7, s26
	s_waitcnt lgkmcnt(2)
	v_bfe_u32 v8, v18, 16, 1
	ds_read2_b32 v[38:39], v23 offset0:214 offset1:222
	v_lshrrev_b32_e32 v7, 16, v7
	v_add3_u32 v8, v18, v8, s26
	ds_read2_b32 v[40:41], v23 offset0:247 offset1:255
	v_and_or_b32 v7, v8, s27, v7
	s_waitcnt lgkmcnt(3)
	v_bfe_u32 v8, v20, 16, 1
	v_add3_u32 v8, v20, v8, s26
	s_waitcnt lgkmcnt(2)
	v_bfe_u32 v9, v36, 16, 1
	v_lshrrev_b32_e32 v8, 16, v8
	v_add3_u32 v9, v36, v9, s26
	v_and_or_b32 v8, v9, s27, v8
	s_waitcnt lgkmcnt(1)
	v_bfe_u32 v9, v38, 16, 1
	v_add3_u32 v9, v38, v9, s26
	s_waitcnt lgkmcnt(0)
	v_bfe_u32 v10, v40, 16, 1
	v_lshrrev_b32_e32 v9, 16, v9
	v_add3_u32 v10, v40, v10, s26
	v_and_or_b32 v9, v10, s27, v9
	v_or_b32_e32 v10, s23, v25
	v_lshlrev_b32_e32 v42, 12, v10
	v_mov_b32_e32 v43, v3
	v_lshl_add_u64 v[42:43], v[12:13], 0, v[42:43]
	global_store_dwordx4 v[42:43], v[6:9], off
	v_bfe_u32 v10, v41, 16, 1
	v_add3_u32 v10, v41, v10, s26
	v_bfe_u32 v6, v15, 16, 1
	v_add3_u32 v6, v15, v6, s26
	v_bfe_u32 v7, v11, 16, 1
	v_lshrrev_b32_e32 v6, 16, v6
	v_add3_u32 v7, v11, v7, s26
	v_and_or_b32 v6, v7, s27, v6
	v_bfe_u32 v7, v17, 16, 1
	v_add3_u32 v7, v17, v7, s26
	v_bfe_u32 v8, v19, 16, 1
	v_lshrrev_b32_e32 v7, 16, v7
	v_add3_u32 v8, v19, v8, s26
	v_and_or_b32 v7, v8, s27, v7
	v_bfe_u32 v8, v21, 16, 1
	v_add3_u32 v8, v21, v8, s26
	v_bfe_u32 v9, v37, 16, 1
	v_lshrrev_b32_e32 v8, 16, v8
	v_add3_u32 v9, v37, v9, s26
	v_and_or_b32 v8, v9, s27, v8
	v_bfe_u32 v9, v39, 16, 1
	v_add3_u32 v9, v39, v9, s26
	v_lshrrev_b32_e32 v9, 16, v9
	v_and_or_b32 v9, v10, s27, v9
	v_or_b32_e32 v10, s23, v26
	v_lshlrev_b32_e32 v10, 12, v10
	v_mov_b32_e32 v11, v3
	v_lshl_add_u64 v[10:11], v[12:13], 0, v[10:11]
	global_store_dwordx4 v[10:11], v[6:9], off
	s_waitcnt lgkmcnt(0)

.LBB0_44:
	v_lshl_add_u64 v[36:37], v[20:21], 0, s[20:21]
	v_lshl_add_u64 v[38:39], v[18:19], 0, s[20:21]
	v_lshl_add_u64 v[40:41], v[16:17], 0, s[20:21]
	v_lshl_add_u64 v[42:43], v[14:15], 0, s[20:21]
	v_lshl_add_u64 v[44:45], v[12:13], 0, s[20:21]
	v_lshl_add_u64 v[46:47], v[10:11], 0, s[20:21]
	v_lshl_add_u64 v[48:49], v[8:9], 0, s[20:21]
	v_lshl_add_u64 v[50:51], v[6:7], 0, s[20:21]
	global_load_dword v52, v[36:37], off nt
	global_load_dword v53, v[38:39], off nt
	global_load_dword v54, v[40:41], off nt
	global_load_dword v55, v[42:43], off nt
	global_load_dword v56, v[44:45], off nt
	global_load_dword v57, v[46:47], off nt
	global_load_dword v58, v[48:49], off nt
	global_load_dword v59, v[50:51], off nt
	s_add_u32 s20, s20, 0x50000
	s_addc_u32 s21, s21, 0
	v_lshl_add_u64 v[36:37], v[20:21], 0, s[20:21]
	v_lshl_add_u64 v[38:39], v[18:19], 0, s[20:21]
	v_lshl_add_u64 v[40:41], v[16:17], 0, s[20:21]
	v_lshl_add_u64 v[42:43], v[14:15], 0, s[20:21]
	v_lshl_add_u64 v[44:45], v[12:13], 0, s[20:21]
	v_lshl_add_u64 v[46:47], v[10:11], 0, s[20:21]
	v_lshl_add_u64 v[48:49], v[8:9], 0, s[20:21]
	v_lshl_add_u64 v[50:51], v[6:7], 0, s[20:21]
	global_load_dword v60, v[36:37], off nt
	global_load_dword v61, v[38:39], off nt
	global_load_dword v62, v[40:41], off nt
	global_load_dword v63, v[42:43], off nt
	global_load_dword v64, v[44:45], off nt
	global_load_dword v65, v[46:47], off nt
	global_load_dword v66, v[48:49], off nt
	global_load_dword v67, v[50:51], off nt
	s_add_u32 s20, s20, 0x50000
	s_addc_u32 s21, s21, 0
	v_add_u32_e32 v36, 0x400, v35
	s_waitcnt vmcnt(14)
	ds_write2_b32 v35, v52, v53 offset1:66
	s_waitcnt vmcnt(12)
	ds_write2_b32 v35, v54, v55 offset0:132 offset1:198
	s_waitcnt vmcnt(10)
	ds_write2_b32 v36, v56, v57 offset0:8 offset1:74
	s_waitcnt vmcnt(8)
	ds_write2_b32 v36, v58, v59 offset0:140 offset1:206
	v_add_u32_e32 v35, 0x840, v35
	v_add_u32_e32 v36, 0x400, v35
	s_waitcnt vmcnt(6)
	ds_write2_b32 v35, v60, v61 offset1:66
	s_waitcnt vmcnt(4)
	ds_write2_b32 v35, v62, v63 offset0:132 offset1:198
	s_waitcnt vmcnt(2)
	ds_write2_b32 v36, v64, v65 offset0:8 offset1:74
	s_waitcnt vmcnt(0)
	ds_write2_b32 v36, v66, v67 offset0:140 offset1:206
	v_add_u32_e32 v35, 0x840, v35
	v_lshl_add_u64 v[36:37], v[20:21], 0, s[20:21]
	v_lshl_add_u64 v[38:39], v[18:19], 0, s[20:21]
	v_lshl_add_u64 v[40:41], v[16:17], 0, s[20:21]
	v_lshl_add_u64 v[42:43], v[14:15], 0, s[20:21]
	v_lshl_add_u64 v[44:45], v[12:13], 0, s[20:21]
	v_lshl_add_u64 v[46:47], v[10:11], 0, s[20:21]
	v_lshl_add_u64 v[48:49], v[8:9], 0, s[20:21]
	v_lshl_add_u64 v[50:51], v[6:7], 0, s[20:21]
	global_load_dword v52, v[36:37], off nt
	global_load_dword v53, v[38:39], off nt
	global_load_dword v54, v[40:41], off nt
	global_load_dword v55, v[42:43], off nt
	global_load_dword v56, v[44:45], off nt
	global_load_dword v57, v[46:47], off nt
	global_load_dword v58, v[48:49], off nt
	global_load_dword v59, v[50:51], off nt
	s_add_u32 s20, s20, 0x50000
	s_addc_u32 s21, s21, 0
	v_lshl_add_u64 v[36:37], v[20:21], 0, s[20:21]
	v_lshl_add_u64 v[38:39], v[18:19], 0, s[20:21]
	v_lshl_add_u64 v[40:41], v[16:17], 0, s[20:21]
	v_lshl_add_u64 v[42:43], v[14:15], 0, s[20:21]
	v_lshl_add_u64 v[44:45], v[12:13], 0, s[20:21]
	v_lshl_add_u64 v[46:47], v[10:11], 0, s[20:21]
	v_lshl_add_u64 v[48:49], v[8:9], 0, s[20:21]
	v_lshl_add_u64 v[50:51], v[6:7], 0, s[20:21]
	global_load_dword v60, v[36:37], off nt
	global_load_dword v61, v[38:39], off nt
	global_load_dword v62, v[40:41], off nt
	global_load_dword v63, v[42:43], off nt
	global_load_dword v64, v[44:45], off nt
	global_load_dword v65, v[46:47], off nt
	global_load_dword v66, v[48:49], off nt
	global_load_dword v67, v[50:51], off nt
	s_add_u32 s20, s20, 0x50000
	s_addc_u32 s21, s21, 0
	v_add_u32_e32 v36, 0x400, v35
	s_waitcnt vmcnt(14)
	ds_write2_b32 v35, v52, v53 offset1:66
	s_waitcnt vmcnt(12)
	ds_write2_b32 v35, v54, v55 offset0:132 offset1:198
	s_waitcnt vmcnt(10)
	ds_write2_b32 v36, v56, v57 offset0:8 offset1:74
	s_waitcnt vmcnt(8)
	ds_write2_b32 v36, v58, v59 offset0:140 offset1:206
	v_add_u32_e32 v35, 0x840, v35
	v_add_u32_e32 v36, 0x400, v35
	s_waitcnt vmcnt(6)
	ds_write2_b32 v35, v60, v61 offset1:66
	s_waitcnt vmcnt(4)
	ds_write2_b32 v35, v62, v63 offset0:132 offset1:198
	s_waitcnt vmcnt(2)
	ds_write2_b32 v36, v64, v65 offset0:8 offset1:74
	s_waitcnt vmcnt(0)
	ds_write2_b32 v36, v66, v67 offset0:140 offset1:206
	v_add_u32_e32 v35, 0x840, v35
	s_waitcnt lgkmcnt(0)
	s_and_b32 s19, 0xffff, s19
	ds_read2_b32 v[10:11], v23 offset1:8
	s_and_b32 s23, 0xffff, s23
	s_lshl_b32 s19, s19, 1
	ds_read2_b32 v[14:15], v23 offset0:33 offset1:41
	s_add_u32 s20, s30, s19
	s_addc_u32 s21, s31, 0
	ds_read2_b32 v[16:17], v23 offset0:66 offset1:74
	v_lshl_add_u64 v[6:7], s[20:21], 0, v[2:3]
	ds_read2_b32 v[18:19], v23 offset0:99 offset1:107
	v_lshl_add_u64 v[12:13], v[6:7], 0, s[14:15]
	s_waitcnt lgkmcnt(3)
	v_bfe_u32 v6, v10, 16, 1
	v_add3_u32 v6, v10, v6, s26
	s_waitcnt lgkmcnt(2)
	v_bfe_u32 v7, v14, 16, 1
	ds_read2_b32 v[20:21], v23 offset0:132 offset1:140
	v_lshrrev_b32_e32 v6, 16, v6
	v_add3_u32 v7, v14, v7, s26
	ds_read2_b32 v[36:37], v23 offset0:165 offset1:173
	v_and_or_b32 v6, v7, s27, v6
	s_waitcnt lgkmcnt(3)
	v_bfe_u32 v7, v16, 16, 1
	v_add3_u32 v7, v16, v7, s26
	s_waitcnt lgkmcnt(2)
	v_bfe_u32 v8, v18, 16, 1
	ds_read2_b32 v[38:39], v23 offset0:198 offset1:206
	v_lshrrev_b32_e32 v7, 16, v7
	v_add3_u32 v8, v18, v8, s26
	ds_read2_b32 v[40:41], v23 offset0:231 offset1:239
	v_and_or_b32 v7, v8, s27, v7
	s_waitcnt lgkmcnt(3)
	v_bfe_u32 v8, v20, 16, 1
	v_add3_u32 v8, v20, v8, s26
	s_waitcnt lgkmcnt(2)
	v_bfe_u32 v9, v36, 16, 1
	v_lshrrev_b32_e32 v8, 16, v8
	v_add3_u32 v9, v36, v9, s26
	v_and_or_b32 v8, v9, s27, v8
	s_waitcnt lgkmcnt(1)
	v_bfe_u32 v9, v38, 16, 1
	v_add3_u32 v9, v38, v9, s26
	s_waitcnt lgkmcnt(0)
	v_bfe_u32 v10, v40, 16, 1
	v_lshrrev_b32_e32 v9, 16, v9
	v_add3_u32 v10, v40, v10, s26
	v_and_or_b32 v9, v10, s27, v9
	v_or_b32_e32 v10, s23, v22
	v_lshlrev_b32_e32 v42, 12, v10
	v_mov_b32_e32 v43, v3
	v_lshl_add_u64 v[42:43], v[12:13], 0, v[42:43]
	global_store_dwordx4 v[42:43], v[6:9], off
	v_bfe_u32 v10, v41, 16, 1
	v_add3_u32 v10, v41, v10, s26
	v_bfe_u32 v6, v11, 16, 1
	v_add3_u32 v6, v11, v6, s26
	v_bfe_u32 v7, v15, 16, 1
	v_lshrrev_b32_e32 v6, 16, v6
	v_add3_u32 v7, v15, v7, s26
	v_and_or_b32 v6, v7, s27, v6
	v_bfe_u32 v7, v17, 16, 1
	v_add3_u32 v7, v17, v7, s26
	v_bfe_u32 v8, v19, 16, 1
	v_lshrrev_b32_e32 v7, 16, v7
	v_add3_u32 v8, v19, v8, s26
	v_and_or_b32 v7, v8, s27, v7
	v_bfe_u32 v8, v21, 16, 1
	v_add3_u32 v8, v21, v8, s26
	v_bfe_u32 v9, v37, 16, 1
	v_lshrrev_b32_e32 v8, 16, v8
	v_add3_u32 v9, v37, v9, s26
	v_and_or_b32 v8, v9, s27, v8
	v_bfe_u32 v9, v39, 16, 1
	v_add3_u32 v9, v39, v9, s26
	v_lshrrev_b32_e32 v9, 16, v9
	v_and_or_b32 v9, v10, s27, v9
	v_or_b32_e32 v10, s23, v24
	v_lshlrev_b32_e32 v10, 12, v10
	v_mov_b32_e32 v11, v3
	ds_read2_b32 v[14:15], v23 offset0:16 offset1:24
	v_lshl_add_u64 v[10:11], v[12:13], 0, v[10:11]
	global_store_dwordx4 v[10:11], v[6:9], off
	ds_read2_b32 v[10:11], v23 offset0:49 offset1:57
	ds_read2_b32 v[16:17], v23 offset0:82 offset1:90
	ds_read2_b32 v[18:19], v23 offset0:115 offset1:123
	s_waitcnt lgkmcnt(3)
	v_bfe_u32 v6, v14, 16, 1
	v_add3_u32 v6, v14, v6, s26
	s_waitcnt lgkmcnt(2)
	v_bfe_u32 v7, v10, 16, 1
	ds_read2_b32 v[20:21], v23 offset0:148 offset1:156
	v_lshrrev_b32_e32 v6, 16, v6
	v_add3_u32 v7, v10, v7, s26
	ds_read2_b32 v[36:37], v23 offset0:181 offset1:189
	v_and_or_b32 v6, v7, s27, v6
	s_waitcnt lgkmcnt(3)
	v_bfe_u32 v7, v16, 16, 1
	v_add3_u32 v7, v16, v7, s26
	s_waitcnt lgkmcnt(2)
	v_bfe_u32 v8, v18, 16, 1
	ds_read2_b32 v[38:39], v23 offset0:214 offset1:222
	v_lshrrev_b32_e32 v7, 16, v7
	v_add3_u32 v8, v18, v8, s26
	ds_read2_b32 v[40:41], v23 offset0:247 offset1:255
	v_and_or_b32 v7, v8, s27, v7
	s_waitcnt lgkmcnt(3)
	v_bfe_u32 v8, v20, 16, 1
	v_add3_u32 v8, v20, v8, s26
	s_waitcnt lgkmcnt(2)
	v_bfe_u32 v9, v36, 16, 1
	v_lshrrev_b32_e32 v8, 16, v8
	v_add3_u32 v9, v36, v9, s26
	v_and_or_b32 v8, v9, s27, v8
	s_waitcnt lgkmcnt(1)
	v_bfe_u32 v9, v38, 16, 1
	v_add3_u32 v9, v38, v9, s26
	s_waitcnt lgkmcnt(0)
	v_bfe_u32 v10, v40, 16, 1
	v_lshrrev_b32_e32 v9, 16, v9
	v_add3_u32 v10, v40, v10, s26
	v_and_or_b32 v9, v10, s27, v9
	v_or_b32_e32 v10, s23, v25
	v_lshlrev_b32_e32 v42, 12, v10
	v_mov_b32_e32 v43, v3
	v_lshl_add_u64 v[42:43], v[12:13], 0, v[42:43]
	global_store_dwordx4 v[42:43], v[6:9], off
	v_bfe_u32 v10, v41, 16, 1
	v_add3_u32 v10, v41, v10, s26
	v_bfe_u32 v6, v15, 16, 1
	v_add3_u32 v6, v15, v6, s26
	v_bfe_u32 v7, v11, 16, 1
	v_lshrrev_b32_e32 v6, 16, v6
	v_add3_u32 v7, v11, v7, s26
	v_and_or_b32 v6, v7, s27, v6
	v_bfe_u32 v7, v17, 16, 1
	v_add3_u32 v7, v17, v7, s26
	v_bfe_u32 v8, v19, 16, 1
	v_lshrrev_b32_e32 v7, 16, v7
	v_add3_u32 v8, v19, v8, s26
	v_and_or_b32 v7, v8, s27, v7
	v_bfe_u32 v8, v21, 16, 1
	v_add3_u32 v8, v21, v8, s26
	v_bfe_u32 v9, v37, 16, 1
	v_lshrrev_b32_e32 v8, 16, v8
	v_add3_u32 v9, v37, v9, s26
	v_and_or_b32 v8, v9, s27, v8
	v_bfe_u32 v9, v39, 16, 1
	v_add3_u32 v9, v39, v9, s26
	v_lshrrev_b32_e32 v9, 16, v9
	v_and_or_b32 v9, v10, s27, v9
	v_or_b32_e32 v10, s23, v26
	v_lshlrev_b32_e32 v10, 12, v10
	v_mov_b32_e32 v11, v3
	v_lshl_add_u64 v[10:11], v[12:13], 0, v[10:11]
	global_store_dwordx4 v[10:11], v[6:9], off
	s_waitcnt lgkmcnt(0)

.LBB0_49:
	v_lshl_add_u64 v[36:37], v[20:21], 0, s[20:21]
	v_lshl_add_u64 v[38:39], v[18:19], 0, s[20:21]
	v_lshl_add_u64 v[40:41], v[16:17], 0, s[20:21]
	v_lshl_add_u64 v[42:43], v[14:15], 0, s[20:21]
	v_lshl_add_u64 v[44:45], v[12:13], 0, s[20:21]
	v_lshl_add_u64 v[46:47], v[10:11], 0, s[20:21]
	v_lshl_add_u64 v[48:49], v[8:9], 0, s[20:21]
	v_lshl_add_u64 v[50:51], v[6:7], 0, s[20:21]
	global_load_dword v52, v[36:37], off nt
	global_load_dword v53, v[38:39], off nt
	global_load_dword v54, v[40:41], off nt
	global_load_dword v55, v[42:43], off nt
	global_load_dword v56, v[44:45], off nt
	global_load_dword v57, v[46:47], off nt
	global_load_dword v58, v[48:49], off nt
	global_load_dword v59, v[50:51], off nt
	s_add_u32 s20, s20, 0x20000
	s_addc_u32 s21, s21, 0
	v_lshl_add_u64 v[36:37], v[20:21], 0, s[20:21]
	v_lshl_add_u64 v[38:39], v[18:19], 0, s[20:21]
	v_lshl_add_u64 v[40:41], v[16:17], 0, s[20:21]
	v_lshl_add_u64 v[42:43], v[14:15], 0, s[20:21]
	v_lshl_add_u64 v[44:45], v[12:13], 0, s[20:21]
	v_lshl_add_u64 v[46:47], v[10:11], 0, s[20:21]
	v_lshl_add_u64 v[48:49], v[8:9], 0, s[20:21]
	v_lshl_add_u64 v[50:51], v[6:7], 0, s[20:21]
	global_load_dword v60, v[36:37], off nt
	global_load_dword v61, v[38:39], off nt
	global_load_dword v62, v[40:41], off nt
	global_load_dword v63, v[42:43], off nt
	global_load_dword v64, v[44:45], off nt
	global_load_dword v65, v[46:47], off nt
	global_load_dword v66, v[48:49], off nt
	global_load_dword v67, v[50:51], off nt
	s_add_u32 s20, s20, 0x20000
	s_addc_u32 s21, s21, 0
	v_add_u32_e32 v36, 0x400, v35
	s_waitcnt vmcnt(14)
	ds_write2_b32 v35, v52, v53 offset1:66
	s_waitcnt vmcnt(12)
	ds_write2_b32 v35, v54, v55 offset0:132 offset1:198
	s_waitcnt vmcnt(10)
	ds_write2_b32 v36, v56, v57 offset0:8 offset1:74
	s_waitcnt vmcnt(8)
	ds_write2_b32 v36, v58, v59 offset0:140 offset1:206
	v_add_u32_e32 v35, 0x840, v35
	v_add_u32_e32 v36, 0x400, v35
	s_waitcnt vmcnt(6)
	ds_write2_b32 v35, v60, v61 offset1:66
	s_waitcnt vmcnt(4)
	ds_write2_b32 v35, v62, v63 offset0:132 offset1:198
	s_waitcnt vmcnt(2)
	ds_write2_b32 v36, v64, v65 offset0:8 offset1:74
	s_waitcnt vmcnt(0)
	ds_write2_b32 v36, v66, v67 offset0:140 offset1:206
	v_add_u32_e32 v35, 0x840, v35
	v_lshl_add_u64 v[36:37], v[20:21], 0, s[20:21]
	v_lshl_add_u64 v[38:39], v[18:19], 0, s[20:21]
	v_lshl_add_u64 v[40:41], v[16:17], 0, s[20:21]
	v_lshl_add_u64 v[42:43], v[14:15], 0, s[20:21]
	v_lshl_add_u64 v[44:45], v[12:13], 0, s[20:21]
	v_lshl_add_u64 v[46:47], v[10:11], 0, s[20:21]
	v_lshl_add_u64 v[48:49], v[8:9], 0, s[20:21]
	v_lshl_add_u64 v[50:51], v[6:7], 0, s[20:21]
	global_load_dword v52, v[36:37], off nt
	global_load_dword v53, v[38:39], off nt
	global_load_dword v54, v[40:41], off nt
	global_load_dword v55, v[42:43], off nt
	global_load_dword v56, v[44:45], off nt
	global_load_dword v57, v[46:47], off nt
	global_load_dword v58, v[48:49], off nt
	global_load_dword v59, v[50:51], off nt
	s_add_u32 s20, s20, 0x20000
	s_addc_u32 s21, s21, 0
	v_lshl_add_u64 v[36:37], v[20:21], 0, s[20:21]
	v_lshl_add_u64 v[38:39], v[18:19], 0, s[20:21]
	v_lshl_add_u64 v[40:41], v[16:17], 0, s[20:21]
	v_lshl_add_u64 v[42:43], v[14:15], 0, s[20:21]
	v_lshl_add_u64 v[44:45], v[12:13], 0, s[20:21]
	v_lshl_add_u64 v[46:47], v[10:11], 0, s[20:21]
	v_lshl_add_u64 v[48:49], v[8:9], 0, s[20:21]
	v_lshl_add_u64 v[50:51], v[6:7], 0, s[20:21]
	global_load_dword v60, v[36:37], off nt
	global_load_dword v61, v[38:39], off nt
	global_load_dword v62, v[40:41], off nt
	global_load_dword v63, v[42:43], off nt
	global_load_dword v64, v[44:45], off nt
	global_load_dword v65, v[46:47], off nt
	global_load_dword v66, v[48:49], off nt
	global_load_dword v67, v[50:51], off nt
	s_add_u32 s20, s20, 0x20000
	s_addc_u32 s21, s21, 0
	v_add_u32_e32 v36, 0x400, v35
	s_waitcnt vmcnt(14)
	ds_write2_b32 v35, v52, v53 offset1:66
	s_waitcnt vmcnt(12)
	ds_write2_b32 v35, v54, v55 offset0:132 offset1:198
	s_waitcnt vmcnt(10)
	ds_write2_b32 v36, v56, v57 offset0:8 offset1:74
	s_waitcnt vmcnt(8)
	ds_write2_b32 v36, v58, v59 offset0:140 offset1:206
	v_add_u32_e32 v35, 0x840, v35
	v_add_u32_e32 v36, 0x400, v35
	s_waitcnt vmcnt(6)
	ds_write2_b32 v35, v60, v61 offset1:66
	s_waitcnt vmcnt(4)
	ds_write2_b32 v35, v62, v63 offset0:132 offset1:198
	s_waitcnt vmcnt(2)
	ds_write2_b32 v36, v64, v65 offset0:8 offset1:74
	s_waitcnt vmcnt(0)
	ds_write2_b32 v36, v66, v67 offset0:140 offset1:206
	v_add_u32_e32 v35, 0x840, v35
	s_waitcnt lgkmcnt(0)
	s_lshl_b32 s20, s22, 5
	ds_read2_b32 v[10:11], v23 offset1:8
	s_and_b32 s23, s20, 0x7e0
	s_lshl_b32 s19, s19, 1
	ds_read2_b32 v[14:15], v23 offset0:33 offset1:41
	s_add_u32 s20, s30, s19
	s_addc_u32 s21, s31, 0
	ds_read2_b32 v[16:17], v23 offset0:66 offset1:74
	v_lshl_add_u64 v[6:7], s[20:21], 0, v[2:3]
	ds_read2_b32 v[18:19], v23 offset0:99 offset1:107
	v_lshl_add_u64 v[12:13], v[6:7], 0, s[16:17]
	s_waitcnt lgkmcnt(3)
	v_bfe_u32 v6, v10, 16, 1
	v_add3_u32 v6, v10, v6, s26
	s_waitcnt lgkmcnt(2)
	v_bfe_u32 v7, v14, 16, 1
	ds_read2_b32 v[20:21], v23 offset0:132 offset1:140
	v_lshrrev_b32_e32 v6, 16, v6
	v_add3_u32 v7, v14, v7, s26
	ds_read2_b32 v[36:37], v23 offset0:165 offset1:173
	v_and_or_b32 v6, v7, s27, v6
	s_waitcnt lgkmcnt(3)
	v_bfe_u32 v7, v16, 16, 1
	v_add3_u32 v7, v16, v7, s26
	s_waitcnt lgkmcnt(2)
	v_bfe_u32 v8, v18, 16, 1
	ds_read2_b32 v[38:39], v23 offset0:198 offset1:206
	v_lshrrev_b32_e32 v7, 16, v7
	v_add3_u32 v8, v18, v8, s26
	ds_read2_b32 v[40:41], v23 offset0:231 offset1:239
	v_and_or_b32 v7, v8, s27, v7
	s_waitcnt lgkmcnt(3)
	v_bfe_u32 v8, v20, 16, 1
	v_add3_u32 v8, v20, v8, s26
	s_waitcnt lgkmcnt(2)
	v_bfe_u32 v9, v36, 16, 1
	v_lshrrev_b32_e32 v8, 16, v8
	v_add3_u32 v9, v36, v9, s26
	v_and_or_b32 v8, v9, s27, v8
	s_waitcnt lgkmcnt(1)
	v_bfe_u32 v9, v38, 16, 1
	v_add3_u32 v9, v38, v9, s26
	s_waitcnt lgkmcnt(0)
	v_bfe_u32 v10, v40, 16, 1
	v_lshrrev_b32_e32 v9, 16, v9
	v_add3_u32 v10, v40, v10, s26
	v_and_or_b32 v9, v10, s27, v9
	v_or_b32_e32 v10, s23, v22
	v_mul_u32_u24_e32 v10, 0x1600, v10
	v_lshlrev_b32_e32 v42, 1, v10
	v_mov_b32_e32 v43, v3
	v_lshl_add_u64 v[42:43], v[12:13], 0, v[42:43]
	global_store_dwordx4 v[42:43], v[6:9], off
	v_bfe_u32 v10, v41, 16, 1
	v_add3_u32 v10, v41, v10, s26
	v_bfe_u32 v6, v11, 16, 1
	v_add3_u32 v6, v11, v6, s26
	v_bfe_u32 v7, v15, 16, 1
	v_lshrrev_b32_e32 v6, 16, v6
	v_add3_u32 v7, v15, v7, s26
	v_and_or_b32 v6, v7, s27, v6
	v_bfe_u32 v7, v17, 16, 1
	v_add3_u32 v7, v17, v7, s26
	v_bfe_u32 v8, v19, 16, 1
	v_lshrrev_b32_e32 v7, 16, v7
	v_add3_u32 v8, v19, v8, s26
	v_and_or_b32 v7, v8, s27, v7
	v_bfe_u32 v8, v21, 16, 1
	v_add3_u32 v8, v21, v8, s26
	v_bfe_u32 v9, v37, 16, 1
	v_lshrrev_b32_e32 v8, 16, v8
	v_add3_u32 v9, v37, v9, s26
	v_and_or_b32 v8, v9, s27, v8
	v_bfe_u32 v9, v39, 16, 1
	v_add3_u32 v9, v39, v9, s26
	v_lshrrev_b32_e32 v9, 16, v9
	v_and_or_b32 v9, v10, s27, v9
	v_or_b32_e32 v10, s23, v24
	v_mul_u32_u24_e32 v10, 0x1600, v10
	v_lshlrev_b32_e32 v10, 1, v10
	v_mov_b32_e32 v11, v3
	ds_read2_b32 v[14:15], v23 offset0:16 offset1:24
	v_lshl_add_u64 v[10:11], v[12:13], 0, v[10:11]
	global_store_dwordx4 v[10:11], v[6:9], off
	ds_read2_b32 v[10:11], v23 offset0:49 offset1:57
	ds_read2_b32 v[16:17], v23 offset0:82 offset1:90
	ds_read2_b32 v[18:19], v23 offset0:115 offset1:123
	s_waitcnt lgkmcnt(3)
	v_bfe_u32 v6, v14, 16, 1
	v_add3_u32 v6, v14, v6, s26
	s_waitcnt lgkmcnt(2)
	v_bfe_u32 v7, v10, 16, 1
	ds_read2_b32 v[20:21], v23 offset0:148 offset1:156
	v_lshrrev_b32_e32 v6, 16, v6
	v_add3_u32 v7, v10, v7, s26
	ds_read2_b32 v[36:37], v23 offset0:181 offset1:189
	v_and_or_b32 v6, v7, s27, v6
	s_waitcnt lgkmcnt(3)
	v_bfe_u32 v7, v16, 16, 1
	v_add3_u32 v7, v16, v7, s26
	s_waitcnt lgkmcnt(2)
	v_bfe_u32 v8, v18, 16, 1
	ds_read2_b32 v[38:39], v23 offset0:214 offset1:222
	v_lshrrev_b32_e32 v7, 16, v7
	v_add3_u32 v8, v18, v8, s26
	ds_read2_b32 v[40:41], v23 offset0:247 offset1:255
	v_and_or_b32 v7, v8, s27, v7
	s_waitcnt lgkmcnt(3)
	v_bfe_u32 v8, v20, 16, 1
	v_add3_u32 v8, v20, v8, s26
	s_waitcnt lgkmcnt(2)
	v_bfe_u32 v9, v36, 16, 1
	v_lshrrev_b32_e32 v8, 16, v8
	v_add3_u32 v9, v36, v9, s26
	v_and_or_b32 v8, v9, s27, v8
	s_waitcnt lgkmcnt(1)
	v_bfe_u32 v9, v38, 16, 1
	v_add3_u32 v9, v38, v9, s26
	s_waitcnt lgkmcnt(0)
	v_bfe_u32 v10, v40, 16, 1
	v_lshrrev_b32_e32 v9, 16, v9
	v_add3_u32 v10, v40, v10, s26
	v_and_or_b32 v9, v10, s27, v9
	v_or_b32_e32 v10, s23, v25
	v_mul_u32_u24_e32 v10, 0x1600, v10
	v_lshlrev_b32_e32 v42, 1, v10
	v_mov_b32_e32 v43, v3
	v_lshl_add_u64 v[42:43], v[12:13], 0, v[42:43]
	global_store_dwordx4 v[42:43], v[6:9], off
	v_bfe_u32 v10, v41, 16, 1
	v_add3_u32 v10, v41, v10, s26
	v_bfe_u32 v6, v15, 16, 1
	v_add3_u32 v6, v15, v6, s26
	v_bfe_u32 v7, v11, 16, 1
	v_lshrrev_b32_e32 v6, 16, v6
	v_add3_u32 v7, v11, v7, s26
	v_and_or_b32 v6, v7, s27, v6
	v_bfe_u32 v7, v17, 16, 1
	v_add3_u32 v7, v17, v7, s26
	v_bfe_u32 v8, v19, 16, 1
	v_lshrrev_b32_e32 v7, 16, v7
	v_add3_u32 v8, v19, v8, s26
	v_and_or_b32 v7, v8, s27, v7
	v_bfe_u32 v8, v21, 16, 1
	v_add3_u32 v8, v21, v8, s26
	v_bfe_u32 v9, v37, 16, 1
	v_lshrrev_b32_e32 v8, 16, v8
	v_add3_u32 v9, v37, v9, s26
	v_and_or_b32 v8, v9, s27, v8
	v_bfe_u32 v9, v39, 16, 1
	v_add3_u32 v9, v39, v9, s26
	v_lshrrev_b32_e32 v9, 16, v9
	v_and_or_b32 v9, v10, s27, v9
	v_or_b32_e32 v10, s23, v26
	v_mul_u32_u24_e32 v10, 0x1600, v10
	v_lshlrev_b32_e32 v10, 1, v10
	v_mov_b32_e32 v11, v3
	v_lshl_add_u64 v[10:11], v[12:13], 0, v[10:11]
	global_store_dwordx4 v[10:11], v[6:9], off
	s_waitcnt lgkmcnt(0)

.LBB0_54:
	v_lshl_add_u64 v[36:37], v[20:21], 0, s[20:21]
	v_lshl_add_u64 v[38:39], v[18:19], 0, s[20:21]
	v_lshl_add_u64 v[40:41], v[16:17], 0, s[20:21]
	v_lshl_add_u64 v[42:43], v[14:15], 0, s[20:21]
	v_lshl_add_u64 v[44:45], v[12:13], 0, s[20:21]
	v_lshl_add_u64 v[46:47], v[10:11], 0, s[20:21]
	v_lshl_add_u64 v[48:49], v[8:9], 0, s[20:21]
	v_lshl_add_u64 v[50:51], v[6:7], 0, s[20:21]
	global_load_dword v52, v[36:37], off nt
	global_load_dword v53, v[38:39], off nt
	global_load_dword v54, v[40:41], off nt
	global_load_dword v55, v[42:43], off nt
	global_load_dword v56, v[44:45], off nt
	global_load_dword v57, v[46:47], off nt
	global_load_dword v58, v[48:49], off nt
	global_load_dword v59, v[50:51], off nt
	s_add_u32 s20, s20, 0x58000
	s_addc_u32 s21, s21, 0
	v_lshl_add_u64 v[36:37], v[20:21], 0, s[20:21]
	v_lshl_add_u64 v[38:39], v[18:19], 0, s[20:21]
	v_lshl_add_u64 v[40:41], v[16:17], 0, s[20:21]
	v_lshl_add_u64 v[42:43], v[14:15], 0, s[20:21]
	v_lshl_add_u64 v[44:45], v[12:13], 0, s[20:21]
	v_lshl_add_u64 v[46:47], v[10:11], 0, s[20:21]
	v_lshl_add_u64 v[48:49], v[8:9], 0, s[20:21]
	v_lshl_add_u64 v[50:51], v[6:7], 0, s[20:21]
	global_load_dword v60, v[36:37], off nt
	global_load_dword v61, v[38:39], off nt
	global_load_dword v62, v[40:41], off nt
	global_load_dword v63, v[42:43], off nt
	global_load_dword v64, v[44:45], off nt
	global_load_dword v65, v[46:47], off nt
	global_load_dword v66, v[48:49], off nt
	global_load_dword v67, v[50:51], off nt
	s_add_u32 s20, s20, 0x58000
	s_addc_u32 s21, s21, 0
	v_add_u32_e32 v36, 0x400, v35
	s_waitcnt vmcnt(14)
	ds_write2_b32 v35, v52, v53 offset1:66
	s_waitcnt vmcnt(12)
	ds_write2_b32 v35, v54, v55 offset0:132 offset1:198
	s_waitcnt vmcnt(10)
	ds_write2_b32 v36, v56, v57 offset0:8 offset1:74
	s_waitcnt vmcnt(8)
	ds_write2_b32 v36, v58, v59 offset0:140 offset1:206
	v_add_u32_e32 v35, 0x840, v35
	v_add_u32_e32 v36, 0x400, v35
	s_waitcnt vmcnt(6)
	ds_write2_b32 v35, v60, v61 offset1:66
	s_waitcnt vmcnt(4)
	ds_write2_b32 v35, v62, v63 offset0:132 offset1:198
	s_waitcnt vmcnt(2)
	ds_write2_b32 v36, v64, v65 offset0:8 offset1:74
	s_waitcnt vmcnt(0)
	ds_write2_b32 v36, v66, v67 offset0:140 offset1:206
	v_add_u32_e32 v35, 0x840, v35
	v_lshl_add_u64 v[36:37], v[20:21], 0, s[20:21]
	v_lshl_add_u64 v[38:39], v[18:19], 0, s[20:21]
	v_lshl_add_u64 v[40:41], v[16:17], 0, s[20:21]
	v_lshl_add_u64 v[42:43], v[14:15], 0, s[20:21]
	v_lshl_add_u64 v[44:45], v[12:13], 0, s[20:21]
	v_lshl_add_u64 v[46:47], v[10:11], 0, s[20:21]
	v_lshl_add_u64 v[48:49], v[8:9], 0, s[20:21]
	v_lshl_add_u64 v[50:51], v[6:7], 0, s[20:21]
	global_load_dword v52, v[36:37], off nt
	global_load_dword v53, v[38:39], off nt
	global_load_dword v54, v[40:41], off nt
	global_load_dword v55, v[42:43], off nt
	global_load_dword v56, v[44:45], off nt
	global_load_dword v57, v[46:47], off nt
	global_load_dword v58, v[48:49], off nt
	global_load_dword v59, v[50:51], off nt
	s_add_u32 s20, s20, 0x58000
	s_addc_u32 s21, s21, 0
	v_lshl_add_u64 v[36:37], v[20:21], 0, s[20:21]
	v_lshl_add_u64 v[38:39], v[18:19], 0, s[20:21]
	v_lshl_add_u64 v[40:41], v[16:17], 0, s[20:21]
	v_lshl_add_u64 v[42:43], v[14:15], 0, s[20:21]
	v_lshl_add_u64 v[44:45], v[12:13], 0, s[20:21]
	v_lshl_add_u64 v[46:47], v[10:11], 0, s[20:21]
	v_lshl_add_u64 v[48:49], v[8:9], 0, s[20:21]
	v_lshl_add_u64 v[50:51], v[6:7], 0, s[20:21]
	global_load_dword v60, v[36:37], off nt
	global_load_dword v61, v[38:39], off nt
	global_load_dword v62, v[40:41], off nt
	global_load_dword v63, v[42:43], off nt
	global_load_dword v64, v[44:45], off nt
	global_load_dword v65, v[46:47], off nt
	global_load_dword v66, v[48:49], off nt
	global_load_dword v67, v[50:51], off nt
	s_add_u32 s20, s20, 0x58000
	s_addc_u32 s21, s21, 0
	v_add_u32_e32 v36, 0x400, v35
	s_waitcnt vmcnt(14)
	ds_write2_b32 v35, v52, v53 offset1:66
	s_waitcnt vmcnt(12)
	ds_write2_b32 v35, v54, v55 offset0:132 offset1:198
	s_waitcnt vmcnt(10)
	ds_write2_b32 v36, v56, v57 offset0:8 offset1:74
	s_waitcnt vmcnt(8)
	ds_write2_b32 v36, v58, v59 offset0:140 offset1:206
	v_add_u32_e32 v35, 0x840, v35
	v_add_u32_e32 v36, 0x400, v35
	s_waitcnt vmcnt(6)
	ds_write2_b32 v35, v60, v61 offset1:66
	s_waitcnt vmcnt(4)
	ds_write2_b32 v35, v62, v63 offset0:132 offset1:198
	s_waitcnt vmcnt(2)
	ds_write2_b32 v36, v64, v65 offset0:8 offset1:74
	s_waitcnt vmcnt(0)
	ds_write2_b32 v36, v66, v67 offset0:140 offset1:206
	v_add_u32_e32 v35, 0x840, v35
	s_waitcnt lgkmcnt(0)
	ds_read2_b32 v[10:11], v23 offset1:8
	ds_read2_b32 v[14:15], v23 offset0:33 offset1:41
	ds_read2_b32 v[16:17], v23 offset0:66 offset1:74
	ds_read2_b32 v[18:19], v23 offset0:99 offset1:107
	ds_read2_b32 v[20:21], v23 offset0:132 offset1:140
	s_waitcnt lgkmcnt(4)
	v_bfe_u32 v6, v10, 16, 1
	v_add3_u32 v6, v10, v6, s26
	s_waitcnt lgkmcnt(3)
	v_bfe_u32 v7, v14, 16, 1
	v_lshrrev_b32_e32 v6, 16, v6
	v_add3_u32 v7, v14, v7, s26
	ds_read2_b32 v[36:37], v23 offset0:165 offset1:173
	v_and_or_b32 v6, v7, s27, v6
	s_waitcnt lgkmcnt(3)
	v_bfe_u32 v7, v16, 16, 1
	v_add3_u32 v7, v16, v7, s26
	s_waitcnt lgkmcnt(2)
	v_bfe_u32 v8, v18, 16, 1
	ds_read2_b32 v[38:39], v23 offset0:198 offset1:206
	v_lshrrev_b32_e32 v7, 16, v7
	v_add3_u32 v8, v18, v8, s26
	ds_read2_b32 v[40:41], v23 offset0:231 offset1:239
	v_and_or_b32 v7, v8, s27, v7
	s_waitcnt lgkmcnt(3)
	v_bfe_u32 v8, v20, 16, 1
	s_lshl_b32 s20, s23, 5
	s_lshl_b32 s21, s23, 6
	v_add3_u32 v8, v20, v8, s26
	s_waitcnt lgkmcnt(2)
	v_bfe_u32 v9, v36, 16, 1
	s_and_b32 s21, s21, 0x3f00
	s_and_b32 s20, s20, 0x60
	v_lshrrev_b32_e32 v8, 16, v8
	v_add3_u32 v9, v36, v9, s26
	s_or_b32 s20, s21, s20
	s_and_b32 s19, 0xffff, s19
	v_and_or_b32 v8, v9, s27, v8
	s_waitcnt lgkmcnt(1)
	v_bfe_u32 v9, v38, 16, 1
	s_or_b32 s23, s20, 0x80
	s_lshl_b32 s19, s19, 1
	v_add3_u32 v9, v38, v9, s26
	s_waitcnt lgkmcnt(0)
	v_bfe_u32 v10, v40, 16, 1
	s_add_u32 s20, s30, s19
	v_lshrrev_b32_e32 v9, 16, v9
	v_add3_u32 v10, v40, v10, s26
	s_addc_u32 s21, s31, 0
	v_and_or_b32 v9, v10, s27, v9
	v_or_b32_e32 v10, s23, v22
	v_lshl_add_u64 v[12:13], s[20:21], 0, v[2:3]
	v_lshlrev_b32_e32 v42, 12, v10
	v_mov_b32_e32 v43, v3
	v_lshl_add_u64 v[42:43], v[12:13], 0, v[42:43]
	global_store_dwordx4 v[42:43], v[6:9], off
	v_bfe_u32 v10, v41, 16, 1
	v_add3_u32 v10, v41, v10, s26
	v_bfe_u32 v6, v11, 16, 1
	v_add3_u32 v6, v11, v6, s26
	v_bfe_u32 v7, v15, 16, 1
	v_lshrrev_b32_e32 v6, 16, v6
	v_add3_u32 v7, v15, v7, s26
	v_and_or_b32 v6, v7, s27, v6
	v_bfe_u32 v7, v17, 16, 1
	v_add3_u32 v7, v17, v7, s26
	v_bfe_u32 v8, v19, 16, 1
	v_lshrrev_b32_e32 v7, 16, v7
	v_add3_u32 v8, v19, v8, s26
	v_and_or_b32 v7, v8, s27, v7
	v_bfe_u32 v8, v21, 16, 1
	v_add3_u32 v8, v21, v8, s26
	v_bfe_u32 v9, v37, 16, 1
	v_lshrrev_b32_e32 v8, 16, v8
	v_add3_u32 v9, v37, v9, s26
	v_and_or_b32 v8, v9, s27, v8
	v_bfe_u32 v9, v39, 16, 1
	v_add3_u32 v9, v39, v9, s26
	v_lshrrev_b32_e32 v9, 16, v9
	v_and_or_b32 v9, v10, s27, v9
	v_or_b32_e32 v10, s23, v24
	v_lshlrev_b32_e32 v10, 12, v10
	v_mov_b32_e32 v11, v3
	ds_read2_b32 v[14:15], v23 offset0:16 offset1:24
	v_lshl_add_u64 v[10:11], v[12:13], 0, v[10:11]
	global_store_dwordx4 v[10:11], v[6:9], off
	ds_read2_b32 v[10:11], v23 offset0:49 offset1:57
	ds_read2_b32 v[16:17], v23 offset0:82 offset1:90
	ds_read2_b32 v[18:19], v23 offset0:115 offset1:123
	s_waitcnt lgkmcnt(3)
	v_bfe_u32 v6, v14, 16, 1
	v_add3_u32 v6, v14, v6, s26
	s_waitcnt lgkmcnt(2)
	v_bfe_u32 v7, v10, 16, 1
	ds_read2_b32 v[20:21], v23 offset0:148 offset1:156
	v_lshrrev_b32_e32 v6, 16, v6
	v_add3_u32 v7, v10, v7, s26
	ds_read2_b32 v[36:37], v23 offset0:181 offset1:189
	v_and_or_b32 v6, v7, s27, v6
	s_waitcnt lgkmcnt(3)
	v_bfe_u32 v7, v16, 16, 1
	v_add3_u32 v7, v16, v7, s26
	s_waitcnt lgkmcnt(2)
	v_bfe_u32 v8, v18, 16, 1
	ds_read2_b32 v[38:39], v23 offset0:214 offset1:222
	v_lshrrev_b32_e32 v7, 16, v7
	v_add3_u32 v8, v18, v8, s26
	ds_read2_b32 v[40:41], v23 offset0:247 offset1:255
	v_and_or_b32 v7, v8, s27, v7
	s_waitcnt lgkmcnt(3)
	v_bfe_u32 v8, v20, 16, 1
	v_add3_u32 v8, v20, v8, s26
	s_waitcnt lgkmcnt(2)
	v_bfe_u32 v9, v36, 16, 1
	v_lshrrev_b32_e32 v8, 16, v8
	v_add3_u32 v9, v36, v9, s26
	v_and_or_b32 v8, v9, s27, v8
	s_waitcnt lgkmcnt(1)
	v_bfe_u32 v9, v38, 16, 1
	v_add3_u32 v9, v38, v9, s26
	s_waitcnt lgkmcnt(0)
	v_bfe_u32 v10, v40, 16, 1
	v_lshrrev_b32_e32 v9, 16, v9
	v_add3_u32 v10, v40, v10, s26
	v_and_or_b32 v9, v10, s27, v9
	v_or_b32_e32 v10, s23, v25
	v_lshlrev_b32_e32 v42, 12, v10
	v_mov_b32_e32 v43, v3
	v_lshl_add_u64 v[42:43], v[12:13], 0, v[42:43]
	global_store_dwordx4 v[42:43], v[6:9], off
	v_bfe_u32 v10, v41, 16, 1
	v_add3_u32 v10, v41, v10, s26
	v_bfe_u32 v6, v15, 16, 1
	v_add3_u32 v6, v15, v6, s26
	v_bfe_u32 v7, v11, 16, 1
	v_lshrrev_b32_e32 v6, 16, v6
	v_add3_u32 v7, v11, v7, s26
	v_and_or_b32 v6, v7, s27, v6
	v_bfe_u32 v7, v17, 16, 1
	v_add3_u32 v7, v17, v7, s26
	v_bfe_u32 v8, v19, 16, 1
	v_lshrrev_b32_e32 v7, 16, v7
	v_add3_u32 v8, v19, v8, s26
	v_and_or_b32 v7, v8, s27, v7
	v_bfe_u32 v8, v21, 16, 1
	v_add3_u32 v8, v21, v8, s26
	v_bfe_u32 v9, v37, 16, 1
	v_lshrrev_b32_e32 v8, 16, v8
	v_add3_u32 v9, v37, v9, s26
	v_and_or_b32 v8, v9, s27, v8
	v_bfe_u32 v9, v39, 16, 1
	v_add3_u32 v9, v39, v9, s26
	v_lshrrev_b32_e32 v9, 16, v9
	v_and_or_b32 v9, v10, s27, v9
	v_or_b32_e32 v10, s23, v26
	v_lshlrev_b32_e32 v10, 12, v10
	v_mov_b32_e32 v11, v3
	v_lshl_add_u64 v[10:11], v[12:13], 0, v[10:11]
	global_store_dwordx4 v[10:11], v[6:9], off
	s_waitcnt lgkmcnt(0)

.LBB0_59:
	v_lshl_add_u64 v[36:37], v[20:21], 0, s[22:23]
	v_lshl_add_u64 v[38:39], v[18:19], 0, s[22:23]
	v_lshl_add_u64 v[40:41], v[16:17], 0, s[22:23]
	v_lshl_add_u64 v[42:43], v[14:15], 0, s[22:23]
	v_lshl_add_u64 v[44:45], v[12:13], 0, s[22:23]
	v_lshl_add_u64 v[46:47], v[10:11], 0, s[22:23]
	v_lshl_add_u64 v[48:49], v[8:9], 0, s[22:23]
	v_lshl_add_u64 v[50:51], v[6:7], 0, s[22:23]
	global_load_dword v52, v[36:37], off nt
	global_load_dword v53, v[38:39], off nt
	global_load_dword v54, v[40:41], off nt
	global_load_dword v55, v[42:43], off nt
	global_load_dword v56, v[44:45], off nt
	global_load_dword v57, v[46:47], off nt
	global_load_dword v58, v[48:49], off nt
	global_load_dword v59, v[50:51], off nt
	s_add_u32 s22, s22, 0x58000
	s_addc_u32 s23, s23, 0
	v_lshl_add_u64 v[36:37], v[20:21], 0, s[22:23]
	v_lshl_add_u64 v[38:39], v[18:19], 0, s[22:23]
	v_lshl_add_u64 v[40:41], v[16:17], 0, s[22:23]
	v_lshl_add_u64 v[42:43], v[14:15], 0, s[22:23]
	v_lshl_add_u64 v[44:45], v[12:13], 0, s[22:23]
	v_lshl_add_u64 v[46:47], v[10:11], 0, s[22:23]
	v_lshl_add_u64 v[48:49], v[8:9], 0, s[22:23]
	v_lshl_add_u64 v[50:51], v[6:7], 0, s[22:23]
	global_load_dword v60, v[36:37], off nt
	global_load_dword v61, v[38:39], off nt
	global_load_dword v62, v[40:41], off nt
	global_load_dword v63, v[42:43], off nt
	global_load_dword v64, v[44:45], off nt
	global_load_dword v65, v[46:47], off nt
	global_load_dword v66, v[48:49], off nt
	global_load_dword v67, v[50:51], off nt
	s_add_u32 s22, s22, 0x58000
	s_addc_u32 s23, s23, 0
	v_add_u32_e32 v36, 0x400, v35
	s_waitcnt vmcnt(14)
	ds_write2_b32 v35, v52, v53 offset1:66
	s_waitcnt vmcnt(12)
	ds_write2_b32 v35, v54, v55 offset0:132 offset1:198
	s_waitcnt vmcnt(10)
	ds_write2_b32 v36, v56, v57 offset0:8 offset1:74
	s_waitcnt vmcnt(8)
	ds_write2_b32 v36, v58, v59 offset0:140 offset1:206
	v_add_u32_e32 v35, 0x840, v35
	v_add_u32_e32 v36, 0x400, v35
	s_waitcnt vmcnt(6)
	ds_write2_b32 v35, v60, v61 offset1:66
	s_waitcnt vmcnt(4)
	ds_write2_b32 v35, v62, v63 offset0:132 offset1:198
	s_waitcnt vmcnt(2)
	ds_write2_b32 v36, v64, v65 offset0:8 offset1:74
	s_waitcnt vmcnt(0)
	ds_write2_b32 v36, v66, v67 offset0:140 offset1:206
	v_add_u32_e32 v35, 0x840, v35
	v_lshl_add_u64 v[36:37], v[20:21], 0, s[22:23]
	v_lshl_add_u64 v[38:39], v[18:19], 0, s[22:23]
	v_lshl_add_u64 v[40:41], v[16:17], 0, s[22:23]
	v_lshl_add_u64 v[42:43], v[14:15], 0, s[22:23]
	v_lshl_add_u64 v[44:45], v[12:13], 0, s[22:23]
	v_lshl_add_u64 v[46:47], v[10:11], 0, s[22:23]
	v_lshl_add_u64 v[48:49], v[8:9], 0, s[22:23]
	v_lshl_add_u64 v[50:51], v[6:7], 0, s[22:23]
	global_load_dword v52, v[36:37], off nt
	global_load_dword v53, v[38:39], off nt
	global_load_dword v54, v[40:41], off nt
	global_load_dword v55, v[42:43], off nt
	global_load_dword v56, v[44:45], off nt
	global_load_dword v57, v[46:47], off nt
	global_load_dword v58, v[48:49], off nt
	global_load_dword v59, v[50:51], off nt
	s_add_u32 s22, s22, 0x58000
	s_addc_u32 s23, s23, 0
	v_lshl_add_u64 v[36:37], v[20:21], 0, s[22:23]
	v_lshl_add_u64 v[38:39], v[18:19], 0, s[22:23]
	v_lshl_add_u64 v[40:41], v[16:17], 0, s[22:23]
	v_lshl_add_u64 v[42:43], v[14:15], 0, s[22:23]
	v_lshl_add_u64 v[44:45], v[12:13], 0, s[22:23]
	v_lshl_add_u64 v[46:47], v[10:11], 0, s[22:23]
	v_lshl_add_u64 v[48:49], v[8:9], 0, s[22:23]
	v_lshl_add_u64 v[50:51], v[6:7], 0, s[22:23]
	global_load_dword v60, v[36:37], off nt
	global_load_dword v61, v[38:39], off nt
	global_load_dword v62, v[40:41], off nt
	global_load_dword v63, v[42:43], off nt
	global_load_dword v64, v[44:45], off nt
	global_load_dword v65, v[46:47], off nt
	global_load_dword v66, v[48:49], off nt
	global_load_dword v67, v[50:51], off nt
	s_add_u32 s22, s22, 0x58000
	s_addc_u32 s23, s23, 0
	v_add_u32_e32 v36, 0x400, v35
	s_waitcnt vmcnt(14)
	ds_write2_b32 v35, v52, v53 offset1:66
	s_waitcnt vmcnt(12)
	ds_write2_b32 v35, v54, v55 offset0:132 offset1:198
	s_waitcnt vmcnt(10)
	ds_write2_b32 v36, v56, v57 offset0:8 offset1:74
	s_waitcnt vmcnt(8)
	ds_write2_b32 v36, v58, v59 offset0:140 offset1:206
	v_add_u32_e32 v35, 0x840, v35
	v_add_u32_e32 v36, 0x400, v35
	s_waitcnt vmcnt(6)
	ds_write2_b32 v35, v60, v61 offset1:66
	s_waitcnt vmcnt(4)
	ds_write2_b32 v35, v62, v63 offset0:132 offset1:198
	s_waitcnt vmcnt(2)
	ds_write2_b32 v36, v64, v65 offset0:8 offset1:74
	s_waitcnt vmcnt(0)
	ds_write2_b32 v36, v66, v67 offset0:140 offset1:206
	v_add_u32_e32 v35, 0x840, v35
	s_waitcnt lgkmcnt(0)
	ds_read2_b32 v[10:11], v23 offset1:8
	ds_read2_b32 v[14:15], v23 offset0:33 offset1:41
	ds_read2_b32 v[16:17], v23 offset0:66 offset1:74
	ds_read2_b32 v[18:19], v23 offset0:99 offset1:107
	ds_read2_b32 v[20:21], v23 offset0:132 offset1:140
	s_waitcnt lgkmcnt(4)
	v_bfe_u32 v6, v10, 16, 1
	v_add3_u32 v6, v10, v6, s26
	s_waitcnt lgkmcnt(3)
	v_bfe_u32 v7, v14, 16, 1
	v_lshrrev_b32_e32 v6, 16, v6
	v_add3_u32 v7, v14, v7, s26
	ds_read2_b32 v[36:37], v23 offset0:165 offset1:173
	v_and_or_b32 v6, v7, s27, v6
	s_waitcnt lgkmcnt(3)
	v_bfe_u32 v7, v16, 16, 1
	v_add3_u32 v7, v16, v7, s26
	s_waitcnt lgkmcnt(2)
	v_bfe_u32 v8, v18, 16, 1
	ds_read2_b32 v[38:39], v23 offset0:198 offset1:206
	s_lshl_b32 s19, s19, 6
	v_lshrrev_b32_e32 v7, 16, v7
	v_add3_u32 v8, v18, v8, s26
	ds_read2_b32 v[40:41], v23 offset0:231 offset1:239
	s_and_b32 s19, s19, 0xffffff00
	s_and_b32 s20, s20, 0x60
	v_and_or_b32 v7, v8, s27, v7
	s_waitcnt lgkmcnt(3)
	v_bfe_u32 v8, v20, 16, 1
	s_or_b32 s20, s20, s19
	s_ashr_i32 s19, s18, 31
	v_add3_u32 v8, v20, v8, s26
	s_waitcnt lgkmcnt(2)
	v_bfe_u32 v9, v36, 16, 1
	s_lshl_b64 s[18:19], s[18:19], 1
	v_lshrrev_b32_e32 v8, 16, v8
	v_add3_u32 v9, v36, v9, s26
	s_add_u32 s18, s30, s18
	v_and_or_b32 v8, v9, s27, v8
	s_waitcnt lgkmcnt(1)
	v_bfe_u32 v9, v38, 16, 1
	v_or_b32_e32 v42, s20, v22
	s_addc_u32 s19, s31, s19
	v_add3_u32 v9, v38, v9, s26
	s_waitcnt lgkmcnt(0)
	v_bfe_u32 v10, v40, 16, 1
	v_ashrrev_i32_e32 v43, 31, v42
	v_lshl_add_u64 v[12:13], s[18:19], 0, v[2:3]
	v_lshrrev_b32_e32 v9, 16, v9
	v_add3_u32 v10, v40, v10, s26
	v_lshlrev_b64 v[42:43], 12, v[42:43]
	v_and_or_b32 v9, v10, s27, v9
	v_lshl_add_u64 v[42:43], v[12:13], 0, v[42:43]
	global_store_dwordx4 v[42:43], v[6:9], off
	v_bfe_u32 v10, v41, 16, 1
	v_add3_u32 v10, v41, v10, s26
	v_bfe_u32 v6, v11, 16, 1
	v_add3_u32 v6, v11, v6, s26
	v_bfe_u32 v7, v15, 16, 1
	v_lshrrev_b32_e32 v6, 16, v6
	v_add3_u32 v7, v15, v7, s26
	v_and_or_b32 v6, v7, s27, v6
	v_bfe_u32 v7, v17, 16, 1
	v_add3_u32 v7, v17, v7, s26
	v_bfe_u32 v8, v19, 16, 1
	v_lshrrev_b32_e32 v7, 16, v7
	v_add3_u32 v8, v19, v8, s26
	v_and_or_b32 v7, v8, s27, v7
	v_bfe_u32 v8, v21, 16, 1
	v_add3_u32 v8, v21, v8, s26
	v_bfe_u32 v9, v37, 16, 1
	v_lshrrev_b32_e32 v8, 16, v8
	v_add3_u32 v9, v37, v9, s26
	v_and_or_b32 v8, v9, s27, v8
	v_bfe_u32 v9, v39, 16, 1
	v_add3_u32 v9, v39, v9, s26
	v_lshrrev_b32_e32 v9, 16, v9
	v_and_or_b32 v9, v10, s27, v9
	v_or_b32_e32 v10, s20, v24
	v_ashrrev_i32_e32 v11, 31, v10
	v_lshlrev_b64 v[10:11], 12, v[10:11]
	ds_read2_b32 v[14:15], v23 offset0:16 offset1:24
	v_lshl_add_u64 v[10:11], v[12:13], 0, v[10:11]
	global_store_dwordx4 v[10:11], v[6:9], off
	ds_read2_b32 v[10:11], v23 offset0:49 offset1:57
	ds_read2_b32 v[16:17], v23 offset0:82 offset1:90
	ds_read2_b32 v[18:19], v23 offset0:115 offset1:123
	s_waitcnt lgkmcnt(3)
	v_bfe_u32 v6, v14, 16, 1
	v_add3_u32 v6, v14, v6, s26
	s_waitcnt lgkmcnt(2)
	v_bfe_u32 v7, v10, 16, 1
	ds_read2_b32 v[20:21], v23 offset0:148 offset1:156
	v_lshrrev_b32_e32 v6, 16, v6
	v_add3_u32 v7, v10, v7, s26
	ds_read2_b32 v[36:37], v23 offset0:181 offset1:189
	v_and_or_b32 v6, v7, s27, v6
	s_waitcnt lgkmcnt(3)
	v_bfe_u32 v7, v16, 16, 1
	v_add3_u32 v7, v16, v7, s26
	s_waitcnt lgkmcnt(2)
	v_bfe_u32 v8, v18, 16, 1
	ds_read2_b32 v[38:39], v23 offset0:214 offset1:222
	v_lshrrev_b32_e32 v7, 16, v7
	v_add3_u32 v8, v18, v8, s26
	ds_read2_b32 v[40:41], v23 offset0:247 offset1:255
	v_and_or_b32 v7, v8, s27, v7
	s_waitcnt lgkmcnt(3)
	v_bfe_u32 v8, v20, 16, 1
	v_add3_u32 v8, v20, v8, s26
	s_waitcnt lgkmcnt(2)
	v_bfe_u32 v9, v36, 16, 1
	v_lshrrev_b32_e32 v8, 16, v8
	v_add3_u32 v9, v36, v9, s26
	v_and_or_b32 v8, v9, s27, v8
	s_waitcnt lgkmcnt(1)
	v_bfe_u32 v9, v38, 16, 1
	v_or_b32_e32 v42, s20, v25
	v_add3_u32 v9, v38, v9, s26
	s_waitcnt lgkmcnt(0)
	v_bfe_u32 v10, v40, 16, 1
	v_ashrrev_i32_e32 v43, 31, v42
	v_lshrrev_b32_e32 v9, 16, v9
	v_add3_u32 v10, v40, v10, s26
	v_lshlrev_b64 v[42:43], 12, v[42:43]
	v_and_or_b32 v9, v10, s27, v9
	v_lshl_add_u64 v[42:43], v[12:13], 0, v[42:43]
	global_store_dwordx4 v[42:43], v[6:9], off
	v_bfe_u32 v10, v41, 16, 1
	v_add3_u32 v10, v41, v10, s26
	v_bfe_u32 v6, v15, 16, 1
	v_add3_u32 v6, v15, v6, s26
	v_bfe_u32 v7, v11, 16, 1
	v_lshrrev_b32_e32 v6, 16, v6
	v_add3_u32 v7, v11, v7, s26
	v_and_or_b32 v6, v7, s27, v6
	v_bfe_u32 v7, v17, 16, 1
	v_add3_u32 v7, v17, v7, s26
	v_bfe_u32 v8, v19, 16, 1
	v_lshrrev_b32_e32 v7, 16, v7
	v_add3_u32 v8, v19, v8, s26
	v_and_or_b32 v7, v8, s27, v7
	v_bfe_u32 v8, v21, 16, 1
	v_add3_u32 v8, v21, v8, s26
	v_bfe_u32 v9, v37, 16, 1
	v_lshrrev_b32_e32 v8, 16, v8
	v_add3_u32 v9, v37, v9, s26
	v_and_or_b32 v8, v9, s27, v8
	v_bfe_u32 v9, v39, 16, 1
	v_add3_u32 v9, v39, v9, s26
	v_lshrrev_b32_e32 v9, 16, v9
	v_and_or_b32 v9, v10, s27, v9
	v_or_b32_e32 v10, s20, v26
	v_ashrrev_i32_e32 v11, 31, v10
	v_lshlrev_b64 v[10:11], 12, v[10:11]
	v_lshl_add_u64 v[10:11], v[12:13], 0, v[10:11]
	global_store_dwordx4 v[10:11], v[6:9], off
	s_waitcnt lgkmcnt(0)
	s_branch .LBB0_10
